# stack10: stack9 with the f32 residual-tile stores of the out-proj/ff2 epilogues kept write-back (same-workgroup reader), all other stores write-through
# speedup vs baseline: 1.0365x; 1.0057x over previous
; #define WAIT_V0() asm volatile("s_waitcnt vmcnt(0)" ::: "memory")
; #define G_STAGE_A(Ap, buf, kt) do { const char* ab_ = (const char*)(Ap) + (size_t)(kt) * 128; \
;       _Pragma("unroll") for (int i = 0; i < 4; ++i) \
;         __builtin_amdgcn_global_load_lds((const unsigned*)(ab_ + soff[i]), (LDSP unsigned*)(G_SA(buf) + wid * 1024 + i * 8192), 16, 0, 0); } while (0)
; #define G_STAGE_B(Bp, buf, kt) do { const char* bb_ = (const char*)(Bp) + (size_t)(kt) * 128; \
;       _Pragma("unroll") for (int i = 0; i < 4; ++i) \
;         __builtin_amdgcn_global_load_lds((const unsigned*)(bb_ + soff[i]), (LDSP unsigned*)(G_SB(buf) + wid * 1024 + i * 8192), 16, 0, 0); } while (0)
; #define G_RDA(AF, buf, ks, mh) do { _Pragma("unroll") for (int m = 0; m < 4; ++m) AF[m] = *(const LDSP bf16x8*)(G_SA(buf) + aoff + ((mh) * 4 + m) * 2048 + (ks) * 1024); } while (0)
; #define G_RDB(BF, buf, ks) do { _Pragma("unroll") for (int n = 0; n < 4; ++n) BF[n] = *(const LDSP bf16x8*)(G_SB(buf) + boff + n * 2048 + (ks) * 1024); } while (0)
; #define G_MMA(AF, BF, mh) do { __builtin_amdgcn_s_setprio(1); \
;             _Pragma("unroll") for (int m = 0; m < 4; ++m) _Pragma("unroll") for (int n = 0; n < 4; ++n) \
;                 acc[(mh) * 4 + m][n] = __builtin_amdgcn_mfma_f32_16x16x32_bf16(BF[n], AF[m], acc[(mh) * 4 + m][n], 0, 0, 0); \
;             __builtin_amdgcn_s_setprio(0); } while (0)
; template <int EK>
; DI void gemm_stream(const Params& p, int l, const bf16_t* __restrict__ A, const bf16_t* __restrict__ Bt, int M, int N, int K, ldsp_t shm) {
;     ...
;         for (int t = 0; t < nt; ++t) {
;             const int cur = t & 1;
;             G_RDA(Aa, cur, 0, 0); G_RDB(Bk0, cur, 0);
;             if (t + 1 < nt) G_STAGE_B(Bb, cur ^ 1, t + 1);
;             else if (has_next) G_STAGE_B(Bb2, cur ^ 1, 0);
;             G_SB0();
;             if (t > 0) G_MMA(Ab_, Bk1, 1);
;             G_SB0();
;             if (t + 1 < nt) G_STAGE_A(Ab, cur ^ 1, t + 1);
;             else if (has_next) G_STAGE_A(Ab2, cur ^ 1, 0);
;             G_RDA(Ab_, cur, 0, 1);
;             G_MMA(Aa, Bk0, 0); G_SB0();
;             G_RDA(Aa, cur, 1, 0); G_RDB(Bk1, cur, 1);
;             G_MMA(Ab_, Bk0, 1); G_SB0();
;             G_RDA(Ab_, cur, 1, 1);
;             G_MMA(Aa, Bk1, 0); G_SB0();
;             asm volatile("s_waitcnt lgkmcnt(0)" ::: "memory");
;             WAIT_V0(); __syncthreads();
;         }
.LBB0_137:
	v_add_u32_e32 v80, 0x12000, v218
	v_add_u32_e32 v84, 0x12800, v218
	v_add_u32_e32 v88, 0x13000, v218
	v_add_u32_e32 v92, 0x13800, v218
	ds_read_b128 v[80:83], v80
	ds_read_b128 v[84:87], v84
	ds_read_b128 v[88:91], v88
	ds_read_b128 v[92:95], v92
	s_setprio 1
	s_waitcnt lgkmcnt(0)
	v_mfma_f32_16x16x32_bf16 v[0:3], v[160:163], v[188:191], v[0:3]
	v_mfma_f32_16x16x32_bf16 v[4:7], v[164:167], v[188:191], v[4:7]
	v_mfma_f32_16x16x32_bf16 v[8:11], v[168:171], v[188:191], v[8:11]
	v_mfma_f32_16x16x32_bf16 v[12:15], v[172:175], v[188:191], v[12:15]
	v_mfma_f32_16x16x32_bf16 v[16:19], v[160:163], v[180:183], v[16:19]
	v_mfma_f32_16x16x32_bf16 v[20:23], v[164:167], v[180:183], v[20:23]
	v_mfma_f32_16x16x32_bf16 v[24:27], v[168:171], v[180:183], v[24:27]
	v_mfma_f32_16x16x32_bf16 v[28:31], v[172:175], v[180:183], v[28:31]
	v_mfma_f32_16x16x32_bf16 v[32:35], v[160:163], v[184:187], v[32:35]
	v_mfma_f32_16x16x32_bf16 v[36:39], v[164:167], v[184:187], v[36:39]
	v_mfma_f32_16x16x32_bf16 v[40:43], v[168:171], v[184:187], v[40:43]
	v_mfma_f32_16x16x32_bf16 v[44:47], v[172:175], v[184:187], v[44:47]
	v_mfma_f32_16x16x32_bf16 v[48:51], v[160:163], v[176:179], v[48:51]
	v_mfma_f32_16x16x32_bf16 v[52:55], v[164:167], v[176:179], v[52:55]
	v_mfma_f32_16x16x32_bf16 v[56:59], v[168:171], v[176:179], v[56:59]
	v_mfma_f32_16x16x32_bf16 v[60:63], v[172:175], v[176:179], v[60:63]
	s_setprio 0
	v_add_u32_e32 v144, 0x10400, v218
	v_add_u32_e32 v148, 0x10c00, v218
	v_add_u32_e32 v152, 0x11400, v218
	v_add_u32_e32 v156, 0x11c00, v218
	v_add_u32_e32 v176, 0x18400, v219
	v_add_u32_e32 v180, 0x18c00, v219
	v_add_u32_e32 v184, 0x19400, v219
	v_add_u32_e32 v188, 0x19c00, v219
	ds_read_b128 v[144:147], v144
	ds_read_b128 v[148:151], v148
	ds_read_b128 v[152:155], v152
	ds_read_b128 v[156:159], v156
	ds_read_b128 v[176:179], v176
	ds_read_b128 v[180:183], v180
	ds_read_b128 v[184:187], v184
	ds_read_b128 v[188:191], v188
	s_setprio 1
	v_mfma_f32_16x16x32_bf16 v[194:197], v[160:163], v[80:83], v[140:143]
	v_mfma_f32_16x16x32_bf16 v[198:201], v[164:167], v[80:83], v[136:139]
	v_mfma_f32_16x16x32_bf16 v[204:207], v[168:171], v[80:83], v[132:135]
	v_mfma_f32_16x16x32_bf16 v[210:213], v[172:175], v[80:83], v[128:131]
	v_mfma_f32_16x16x32_bf16 v[214:217], v[160:163], v[84:87], v[124:127]
	v_mfma_f32_16x16x32_bf16 v[220:223], v[164:167], v[84:87], v[120:123]
	v_mfma_f32_16x16x32_bf16 v[224:227], v[168:171], v[84:87], v[116:119]
	v_mfma_f32_16x16x32_bf16 v[228:231], v[172:175], v[84:87], v[112:115]
	v_mfma_f32_16x16x32_bf16 v[232:235], v[160:163], v[88:91], v[108:111]
	v_mfma_f32_16x16x32_bf16 v[236:239], v[164:167], v[88:91], v[104:107]
	v_mfma_f32_16x16x32_bf16 v[240:243], v[168:171], v[88:91], v[100:103]
	v_mfma_f32_16x16x32_bf16 v[244:247], v[172:175], v[88:91], v[96:99]
	v_mfma_f32_16x16x32_bf16 v[160:163], v[160:163], v[92:95], v[64:67]
	v_mfma_f32_16x16x32_bf16 v[164:167], v[164:167], v[92:95], v[68:71]
	v_mfma_f32_16x16x32_bf16 v[168:171], v[168:171], v[92:95], v[72:75]
	v_mfma_f32_16x16x32_bf16 v[172:175], v[172:175], v[92:95], v[76:79]
	s_setprio 0
	v_add_u32_e32 v64, 0x12400, v218
	v_add_u32_e32 v68, 0x12c00, v218
	ds_read_b128 v[64:67], v64
	ds_read_b128 v[248:251], v68
	v_add_u32_e32 v68, 0x13400, v218
	v_add_u32_e32 v72, 0x13c00, v218
	ds_read_b128 v[68:71], v68
	ds_read_b128 v[72:75], v72
	s_setprio 1
	s_waitcnt lgkmcnt(0)
	v_mfma_f32_16x16x32_bf16 v[140:143], v[176:179], v[144:147], v[0:3]
	v_mfma_f32_16x16x32_bf16 v[136:139], v[180:183], v[144:147], v[4:7]
	v_mfma_f32_16x16x32_bf16 v[132:135], v[184:187], v[144:147], v[8:11]
	v_mfma_f32_16x16x32_bf16 v[128:131], v[188:191], v[144:147], v[12:15]
	v_mfma_f32_16x16x32_bf16 v[124:127], v[176:179], v[148:151], v[16:19]
	v_mfma_f32_16x16x32_bf16 v[120:123], v[180:183], v[148:151], v[20:23]
	v_mfma_f32_16x16x32_bf16 v[116:119], v[184:187], v[148:151], v[24:27]
	v_mfma_f32_16x16x32_bf16 v[112:115], v[188:191], v[148:151], v[28:31]
	v_mfma_f32_16x16x32_bf16 v[108:111], v[176:179], v[152:155], v[32:35]
	v_mfma_f32_16x16x32_bf16 v[104:107], v[180:183], v[152:155], v[36:39]
	v_mfma_f32_16x16x32_bf16 v[100:103], v[184:187], v[152:155], v[40:43]
	v_mfma_f32_16x16x32_bf16 v[96:99], v[188:191], v[152:155], v[44:47]
	v_mfma_f32_16x16x32_bf16 v[92:95], v[176:179], v[156:159], v[48:51]
	v_mfma_f32_16x16x32_bf16 v[88:91], v[180:183], v[156:159], v[52:55]
	v_mfma_f32_16x16x32_bf16 v[84:87], v[184:187], v[156:159], v[56:59]
	v_mfma_f32_16x16x32_bf16 v[80:83], v[188:191], v[156:159], v[60:63]
	s_setprio 0
	s_waitcnt lgkmcnt(0)
	s_waitcnt vmcnt(0)
	s_waitcnt vmcnt(0)
	s_barrier
; #define G_SB0() __builtin_amdgcn_sched_barrier(0)
;     static DI void run(const f32x4 (&acc)[8][4], const TileCtx& tc, const Params& p, ldsp_t wb) {
;         constexpr int GI = EK == 1 ? 2 : 5;
;         const int cond = tc.brow < NLAT ? (tc.brow >> 12) : 4;
;         const float* gate = p.mod + ((size_t)tc.l * 5 + cond) * 6144 + GI * DM;
;         const int col0 = tc.bcol + tc.wc * 64 + tc.fq * 4;
;         const bool has_next = EK == 1 || tc.l + 1 < DEPTH;
;         const int ln = EK == 1 ? tc.l : (has_next ? tc.l + 1 : tc.l);
;         const float* gnx = (EK == 1 ? p.norm2_g : p.norm1_g) + (size_t)ln * DM + col0;
;         const float* scn = p.mod + ((size_t)ln * 5 + cond) * 6144 + (EK == 1 ? 4 : 1) * DM + col0;
;         float* ssp = p.ss + (size_t)(ln * 2 + (EK == 1 ? 1 : 0)) * NTOK * 16 + (tc.bcol >> 8) * 4 + tc.wc;
;         f32x4 gv[4], av[4];
; #pragma unroll
;         for (int n = 0; n < 4; ++n) {
;             gv[n] = *(const f32x4*)(gate + col0 + n * 16);
;             const f32x4 g1 = *(const f32x4*)(gnx + n * 16), s1 = *(const f32x4*)(scn + n * 16);
;             av[n] = g1 * (1.f + s1);
;         }
; #pragma unroll
;         for (int h = 0; h < 2; ++h) {
; #pragma unroll
;             for (int mm = 0; mm < 4; ++mm) { __builtin_amdgcn_sched_barrier(0);
;                 const int m = h * 4 + mm;
;                 const int row = tc.brow + tc.wr * 128 + m * 16 + tc.fr;
;                 float* xr = xrow_ptr(p, row) + col0;
;                 const float* xs = (EK == 1 && tc.l == 0) ? p.x + (size_t)row * DM + col0 : xr;
;                 float part = 0.f;
; #pragma unroll
;                 for (int n = 0; n < 4; ++n) {
;                     f32x4 xv = *(const f32x4*)(xs + n * 16);
; template <int EK>
; DI void gemm_stream(const Params& p, int l, const bf16_t* __restrict__ A, const bf16_t* __restrict__ Bt, int M, int N, int K, ldsp_t shm) {
;     ...
;         G_MMA(Ab_, Bk1, 1);
;         G_SB0();
;         {
;             int tid2 = threadIdx.x, pme = pm, pne = pn;
;             asm volatile("" : "+v"(tid2), "+s"(pme), "+s"(pne));
;             TileCtx tc;
;             tc.wid = tid2 >> 6; tc.lane = tid2 & 63; tc.wr = tc.wid >> 2; tc.wc = tc.wid & 3; tc.fr = tc.lane & 15; tc.fq = tc.lane >> 4; tc.l = l;
;             tc.brow = pme * 256; tc.bcol = pne * 256; tc.pn = pne;
	s_setprio 1
	v_mfma_f32_16x16x32_bf16 v[76:79], v[176:179], v[64:67], v[194:197]
	v_mfma_f32_16x16x32_bf16 v[198:201], v[180:183], v[64:67], v[198:201]
	v_mfma_f32_16x16x32_bf16 v[194:197], v[184:187], v[64:67], v[204:207]
	v_mfma_f32_16x16x32_bf16 v[64:67], v[188:191], v[64:67], v[210:213]
	v_mfma_f32_16x16x32_bf16 v[60:63], v[176:179], v[248:251], v[214:217]
	v_mfma_f32_16x16x32_bf16 v[56:59], v[180:183], v[248:251], v[220:223]
	v_mfma_f32_16x16x32_bf16 v[52:55], v[184:187], v[248:251], v[224:227]
	v_mfma_f32_16x16x32_bf16 v[48:51], v[188:191], v[248:251], v[228:231]
	v_mfma_f32_16x16x32_bf16 v[44:47], v[176:179], v[68:71], v[232:235]
	v_mfma_f32_16x16x32_bf16 v[40:43], v[180:183], v[68:71], v[236:239]
	v_mfma_f32_16x16x32_bf16 v[36:39], v[184:187], v[68:71], v[240:243]
	v_mfma_f32_16x16x32_bf16 v[32:35], v[188:191], v[68:71], v[244:247]
	v_mfma_f32_16x16x32_bf16 v[16:19], v[176:179], v[72:75], v[160:163]
	v_mfma_f32_16x16x32_bf16 v[12:15], v[180:183], v[72:75], v[164:167]
	v_mfma_f32_16x16x32_bf16 v[8:11], v[184:187], v[72:75], v[168:171]
	v_mfma_f32_16x16x32_bf16 v[0:3], v[188:191], v[72:75], v[172:175]
	s_setprio 0
	v_mov_b32_e32 v177, v252
	s_lshl_b32 s41, s88, 8
	s_min_i32 s6, s41, 0x4000
	s_ashr_i32 s6, s6, 12
	v_readlane_b32 s8, v255, 10
	s_lshl_b32 s38, s87, 8
	s_ashr_i32 s7, s6, 31
	s_mul_i32 s39, s8, 5
	s_add_u32 s6, s39, s6
	s_mul_hi_i32 s39, s8, 5
	v_ashrrev_i32_e32 v144, 6, v177
	s_addc_u32 s7, s39, s7
	v_mov_b64_e32 v[4:5], s[66:67]
	v_mov_b32_e32 v6, 0x6000
	v_and_b32_e32 v145, 3, v144
	s_mul_i32 s39, s7, 0x6000
	v_mad_u64_u32 v[4:5], s[6:7], s6, v6, v[4:5]
	v_lshrrev_b32_e32 v6, 2, v177
	v_lshlrev_b32_e32 v172, 6, v145
	v_and_b32_e32 v6, 12, v6
	v_or3_b32 v6, v6, s38, v172
	v_ashrrev_i32_e32 v7, 31, v6
	v_add_u32_e32 v5, s39, v5
	v_lshlrev_b64 v[150:151], 2, v[6:7]
	v_lshl_add_u64 v[4:5], v[4:5], 0, v[150:151]
	v_add_co_u32_e32 v20, vcc, s33, v4
	s_mov_b64 s[6:7], 0x4000
	s_nop 0
	v_addc_co_u32_e32 v21, vcc, 0, v5, vcc
	global_load_dwordx4 v[68:71], v[20:21], off
	v_lshl_add_u64 v[20:21], v[4:5], 0, s[6:7]
	s_movk_i32 s6, 0x2000
	v_lshl_add_u64 v[6:7], s[34:35], 0, v[150:151]
	global_load_dwordx4 v[72:75], v[20:21], off offset:64
	global_load_dwordx4 v[146:149], v[6:7], off
	global_load_dwordx4 v[152:155], v[20:21], off offset:128
	global_load_dwordx4 v[156:159], v[20:21], off offset:192
	v_add_co_u32_e32 v20, vcc, s6, v4
	s_mov_b64 s[6:7], 0x2000
	s_nop 0
	v_addc_co_u32_e32 v21, vcc, 0, v5, vcc
	global_load_dwordx4 v[164:167], v[6:7], off offset:64
	global_load_dwordx4 v[28:31], v[20:21], off
	global_load_dwordx4 v[178:181], v[6:7], off offset:128
	v_lshl_add_u64 v[4:5], v[4:5], 0, s[6:7]
	global_load_dwordx4 v[182:185], v[6:7], off offset:192
	global_load_dwordx4 v[24:27], v[4:5], off offset:64
	global_load_dwordx4 v[20:23], v[4:5], off offset:128
	s_nop 0
	global_load_dwordx4 v[4:7], v[4:5], off offset:192
	s_lshl_b32 s6, s87, 2
	v_xor_b32_e32 v230, 16, v202
	s_ashr_i32 s7, s6, 31
	v_cmp_lt_i32_e32 vcc, v230, v203
	s_lshl_b64 s[6:7], s[6:7], 2
	s_add_u32 s6, s31, s6
	v_cndmask_b32_e32 v160, v202, v230, vcc
	v_cmp_lt_i32_e32 vcc, v209, v203
	v_lshlrev_b32_e32 v170, 2, v160
	v_mov_b32_e32 v160, 0x10000
	v_cndmask_b32_e32 v171, v202, v209, vcc
	v_lshlrev_b32_e32 v192, 2, v145
	s_addc_u32 s7, s45, s7
	v_and_b32_e32 v175, 63, v177
	v_and_b32_e32 v173, 15, v177
	v_lshl_add_u32 v176, v144, 13, v160
	v_lshl_add_u64 v[144:145], s[6:7], 0, v[192:193]
	v_lshlrev_b32_e32 v171, 2, v171
	v_readlane_b32 s9, v255, 11
	s_waitcnt vmcnt(11)
	v_pk_add_f32 v[70:71], v[70:71], 1.0 op_sel_hi:[1,0]
	v_pk_add_f32 v[68:69], v[68:69], 1.0 op_sel_hi:[1,0]
	s_waitcnt vmcnt(10)
	v_pk_add_f32 v[74:75], v[74:75], 1.0 op_sel_hi:[1,0]
	v_pk_add_f32 v[72:73], v[72:73], 1.0 op_sel_hi:[1,0]
	s_waitcnt vmcnt(8)
	v_pk_add_f32 v[154:155], v[154:155], 1.0 op_sel_hi:[1,0]
	v_pk_add_f32 v[168:169], v[152:153], 1.0 op_sel_hi:[1,0]
	s_waitcnt vmcnt(7)
	v_pk_add_f32 v[186:187], v[158:159], 1.0 op_sel_hi:[1,0]
	v_pk_add_f32 v[188:189], v[156:157], 1.0 op_sel_hi:[1,0]
	v_pk_mul_f32 v[160:161], v[148:149], v[70:71]
	v_pk_mul_f32 v[162:163], v[146:147], v[68:69]
	s_waitcnt vmcnt(6)
	v_pk_mul_f32 v[156:157], v[166:167], v[74:75]
	v_pk_mul_f32 v[158:159], v[164:165], v[72:73]
	s_waitcnt vmcnt(4)
	v_pk_mul_f32 v[152:153], v[180:181], v[154:155]
	v_pk_mul_f32 v[154:155], v[178:179], v[168:169]
	s_waitcnt vmcnt(3)
	v_pk_mul_f32 v[146:147], v[184:185], v[186:187]
	v_pk_mul_f32 v[148:149], v[182:183], v[188:189]
	v_ashrrev_i32_e32 v68, 1, v177
	v_and_b32_e32 v174, 0xffffff80, v68
	v_add_u32_e32 v164, s41, v174
	v_or_b32_e32 v166, v164, v173
	v_cmp_gt_i32_e32 vcc, s33, v166
	v_add_u32_e32 v68, 0xffffc000, v166
	v_ashrrev_i32_e32 v167, 31, v166
	v_mov_b32_e32 v70, s71
	v_mov_b32_e32 v71, s55
	v_cndmask_b32_e32 v69, 0, v167, vcc
	v_cndmask_b32_e32 v68, v68, v166, vcc
	v_cndmask_b32_e32 v71, v70, v71, vcc
	v_mov_b32_e32 v70, s70
	v_mov_b32_e32 v72, s54
	v_cndmask_b32_e32 v70, v70, v72, vcc
	v_lshlrev_b64 v[68:69], 12, v[68:69]
	v_readlane_b32 s8, v254, 50
	v_lshl_add_u64 v[68:69], v[70:71], 0, v[68:69]
	v_lshlrev_b64 v[70:71], 12, v[166:167]
	v_readlane_b32 s9, v254, 51
	v_lshl_add_u64 v[168:169], v[68:69], 0, v[150:151]
	v_bfe_u32 v75, v177, 5, 1
	v_lshl_add_u64 v[70:71], s[8:9], 0, v[70:71]
	v_cndmask_b32_e64 v69, v69, v71, s[4:5]
	v_cndmask_b32_e64 v68, v68, v70, s[4:5]
	v_lshl_add_u64 v[72:73], v[68:69], 0, v[150:151]
	global_load_dwordx4 v[68:71], v[72:73], off
	global_load_dwordx4 v[232:235], v[72:73], off offset:64
	global_load_dwordx4 v[236:239], v[72:73], off offset:128
	global_load_dwordx4 v[240:243], v[72:73], off offset:192
	v_cmp_gt_u32_e32 vcc, 16, v175
	v_readlane_b32 s10, v254, 52
	v_readlane_b32 s11, v254, 53
	v_readlane_b32 s12, v254, 54
	v_readlane_b32 s13, v254, 55
	v_readlane_b32 s14, v254, 56
	v_readlane_b32 s15, v254, 57
	v_readlane_b32 s16, v254, 58
	v_readlane_b32 s17, v254, 59
	v_readlane_b32 s18, v254, 60
	v_readlane_b32 s19, v254, 61
	v_readlane_b32 s20, v254, 62
	v_readlane_b32 s21, v254, 63
	v_readlane_b32 s22, v255, 0
	v_readlane_b32 s23, v255, 1
	s_waitcnt vmcnt(3)
; DI unsigned pk2(float a, float b) { f32x2 v = {a, b}; bf2_t r = __builtin_convertvector(v, bf2_t); return __builtin_bit_cast(unsigned, r); }
;     static DI void run(const f32x4 (&acc)[8][4], const TileCtx& tc, const Params& p, ldsp_t wb) {
;     ...
;             for (int mm = 0; mm < 4; ++mm) { __builtin_amdgcn_sched_barrier(0);
;                 const int m = h * 4 + mm;
;                 const int row = tc.brow + tc.wr * 128 + m * 16 + tc.fr;
;                 float* xr = xrow_ptr(p, row) + col0;
;                 const float* xs = (EK == 1 && tc.l == 0) ? p.x + (size_t)row * DM + col0 : xr;
;                 float part = 0.f;
; #pragma unroll
;                 for (int n = 0; n < 4; ++n) {
;                     f32x4 xv = *(const f32x4*)(xs + n * 16);
;                     xv += gv[n] * acc[m][n];
;                     *(f32x4*)(xr + n * 16) = xv;
;                     if (has_next) {
;                         part += xv[0] * xv[0] + xv[1] * xv[1] + xv[2] * xv[2] + xv[3] * xv[3];
;                         const f32x4 hv = xv * av[n];
;                         u32x2 w; w[0] = pk2(hv[0], hv[1]); w[1] = pk2(hv[2], hv[3]);
;                         wave_put(wb, mm * 16 + tc.fr, n, tc.fq, w);
;                     }
;                 }
;                 if (has_next) {
;                     part += __shfl_xor(part, 16);
;                     part += __shfl_xor(part, 32);
;                     if (tc.fq == 0) ssp[(size_t)row * 16] = part;
;                 }
	v_pk_fma_f32 v[68:69], v[140:141], v[28:29], v[68:69]
	s_nop 0
	v_mul_f32_e32 v74, v69, v69
	v_pk_fma_f32 v[70:71], v[142:143], v[30:31], v[70:71]
	v_fmac_f32_e32 v74, v68, v68
	v_fmac_f32_e32 v74, v70, v70
	global_store_dwordx4 v[168:169], v[68:71], off
	v_fmac_f32_e32 v74, v71, v71
	v_lshl_or_b32 v142, v173, 7, v176
	v_pk_mul_f32 v[70:71], v[160:161], v[70:71]
	v_pk_mul_f32 v[68:69], v[162:163], v[68:69]
	v_and_b32_e32 v143, 7, v177
	v_cvt_pk_bf16_f32 v68, v68, v69
	v_cvt_pk_bf16_f32 v69, v70, v71
	v_bitop3_b32 v70, v75, v177, 7 bitop3:0x78
	v_lshl_or_b32 v141, v70, 4, v142
	v_lshrrev_b32_e32 v70, 1, v177
	v_and_b32_e32 v140, 8, v70
	v_or_b32_e32 v70, v141, v140
	ds_write_b64 v70, v[68:69]
	s_nop 1
	s_waitcnt vmcnt(3)
	v_pk_fma_f32 v[68:69], v[136:137], v[24:25], v[232:233]
	s_nop 0
	v_mul_f32_e32 v136, v69, v69
	v_pk_fma_f32 v[70:71], v[138:139], v[26:27], v[234:235]
	v_fmac_f32_e32 v136, v68, v68
	v_fmac_f32_e32 v136, v70, v70
	global_store_dwordx4 v[168:169], v[68:71], off offset:64
	v_fmac_f32_e32 v136, v71, v71
	v_add_f32_e32 v74, v74, v136
	v_pk_mul_f32 v[70:71], v[156:157], v[70:71]
	v_pk_mul_f32 v[68:69], v[158:159], v[68:69]
	s_nop 0
	v_cvt_pk_bf16_f32 v68, v68, v69
	v_cvt_pk_bf16_f32 v69, v70, v71
	v_bitop3_b32 v70, v75, v143, 2 bitop3:0x36
	v_lshl_or_b32 v136, v70, 4, v142
	v_or_b32_e32 v70, v136, v140
	ds_write_b64 v70, v[68:69]
	s_nop 1
	s_waitcnt vmcnt(3)
	v_pk_fma_f32 v[68:69], v[132:133], v[20:21], v[236:237]
	s_nop 0
	v_mul_f32_e32 v132, v69, v69
	v_pk_fma_f32 v[70:71], v[134:135], v[22:23], v[238:239]
	v_fmac_f32_e32 v132, v68, v68
	v_fmac_f32_e32 v132, v70, v70
	global_store_dwordx4 v[168:169], v[68:71], off offset:128
	v_fmac_f32_e32 v132, v71, v71
	v_add_f32_e32 v74, v74, v132
	v_pk_mul_f32 v[70:71], v[152:153], v[70:71]
	v_pk_mul_f32 v[68:69], v[154:155], v[68:69]
	s_nop 0
	v_cvt_pk_bf16_f32 v68, v68, v69
	v_cvt_pk_bf16_f32 v69, v70, v71
	v_bitop3_b32 v70, v75, v143, 4 bitop3:0x36
	v_lshl_or_b32 v133, v70, 4, v142
	v_or_b32_e32 v70, v133, v140
	ds_write_b64 v70, v[68:69]
	s_nop 1
	s_waitcnt vmcnt(3)
	v_pk_fma_f32 v[68:69], v[128:129], v[4:5], v[240:241]
	s_nop 0
	v_mul_f32_e32 v72, v69, v69
	v_pk_fma_f32 v[70:71], v[130:131], v[6:7], v[242:243]
	v_fmac_f32_e32 v72, v68, v68
	v_fmac_f32_e32 v72, v70, v70
	global_store_dwordx4 v[168:169], v[68:71], off offset:192
	v_fmac_f32_e32 v72, v71, v71
	v_add_f32_e32 v72, v74, v72
	v_pk_mul_f32 v[70:71], v[146:147], v[70:71]
	v_pk_mul_f32 v[68:69], v[148:149], v[68:69]
	s_nop 0
	v_cvt_pk_bf16_f32 v68, v68, v69
	v_cvt_pk_bf16_f32 v69, v70, v71
	v_bitop3_b32 v70, v75, v143, 6 bitop3:0x36
	v_lshl_or_b32 v134, v70, 4, v142
	v_or_b32_e32 v70, v134, v140
	ds_write_b64 v70, v[68:69]
	ds_bpermute_b32 v68, v170, v72
	s_waitcnt lgkmcnt(0)
	v_add_f32_e32 v128, v72, v68
	ds_bpermute_b32 v129, v171, v128
	s_and_saveexec_b64 s[6:7], vcc
	s_cbranch_execz .LBB0_139
	v_lshlrev_b64 v[68:69], 6, v[166:167]
	s_waitcnt lgkmcnt(0)
	v_add_f32_e32 v70, v128, v129
	v_lshl_add_u64 v[68:69], v[144:145], 0, v[68:69]
	global_store_dword v[68:69], v70, off sc1
.LBB0_139:
	s_or_b64 exec, exec, s[6:7]
	v_or_b32_e32 v68, s41, v173
	v_add_u32_e32 v132, v174, v68
	v_add_u32_e32 v128, 16, v132
	v_cmp_gt_i32_e64 s[6:7], s33, v128
	v_add_u32_e32 v68, 0xffffc010, v132
	s_waitcnt lgkmcnt(0)
	v_ashrrev_i32_e32 v129, 31, v128
	v_mov_b32_e32 v70, s71
	v_mov_b32_e32 v71, s55
	v_cndmask_b32_e64 v69, 0, v129, s[6:7]
	v_cndmask_b32_e64 v68, v68, v128, s[6:7]
	v_cndmask_b32_e64 v71, v70, v71, s[6:7]
	v_mov_b32_e32 v70, s70
	v_mov_b32_e32 v72, s54
	v_cndmask_b32_e64 v70, v70, v72, s[6:7]
	v_lshlrev_b64 v[68:69], 12, v[68:69]
	v_readlane_b32 s8, v254, 50
	v_lshl_add_u64 v[68:69], v[70:71], 0, v[68:69]
	v_lshlrev_b64 v[70:71], 12, v[128:129]
	v_readlane_b32 s9, v254, 51
	v_lshl_add_u64 v[130:131], v[68:69], 0, v[150:151]
	v_readlane_b32 s10, v254, 52
	v_lshl_add_u64 v[70:71], s[8:9], 0, v[70:71]
	v_cndmask_b32_e64 v69, v69, v71, s[4:5]
	v_cndmask_b32_e64 v68, v68, v70, s[4:5]
	v_lshl_add_u64 v[72:73], v[68:69], 0, v[150:151]
	global_load_dwordx4 v[68:71], v[72:73], off
	global_load_dwordx4 v[232:235], v[72:73], off offset:64
	global_load_dwordx4 v[236:239], v[72:73], off offset:128
	global_load_dwordx4 v[240:243], v[72:73], off offset:192
	v_readlane_b32 s11, v254, 53
	v_readlane_b32 s12, v254, 54
	v_readlane_b32 s13, v254, 55
	v_readlane_b32 s14, v254, 56
	v_readlane_b32 s15, v254, 57
	v_readlane_b32 s16, v254, 58
	v_readlane_b32 s17, v254, 59
	v_readlane_b32 s18, v254, 60
	v_readlane_b32 s19, v254, 61
	v_readlane_b32 s20, v254, 62
	v_readlane_b32 s21, v254, 63
	v_readlane_b32 s22, v255, 0
	v_readlane_b32 s23, v255, 1
	s_waitcnt vmcnt(3)
	v_pk_fma_f32 v[68:69], v[124:125], v[28:29], v[68:69]
	s_nop 0
	v_mul_f32_e32 v74, v69, v69
	v_pk_fma_f32 v[70:71], v[126:127], v[30:31], v[70:71]
	v_fmac_f32_e32 v74, v68, v68
	v_fmac_f32_e32 v74, v70, v70
	global_store_dwordx4 v[130:131], v[68:71], off
	v_fmac_f32_e32 v74, v71, v71
	v_add_u32_e32 v124, v141, v140
	v_pk_mul_f32 v[70:71], v[160:161], v[70:71]
	v_pk_mul_f32 v[68:69], v[162:163], v[68:69]
	s_nop 0
	v_cvt_pk_bf16_f32 v68, v68, v69
	v_cvt_pk_bf16_f32 v69, v70, v71
	ds_write_b64 v124, v[68:69] offset:2048
	s_nop 1
	s_waitcnt vmcnt(3)
	v_pk_fma_f32 v[68:69], v[120:121], v[24:25], v[232:233]
	s_nop 0
	v_mul_f32_e32 v75, v69, v69
	v_pk_fma_f32 v[70:71], v[122:123], v[26:27], v[234:235]
	v_fmac_f32_e32 v75, v68, v68
	v_fmac_f32_e32 v75, v70, v70
	global_store_dwordx4 v[130:131], v[68:71], off offset:64
	v_fmac_f32_e32 v75, v71, v71
	v_add_u32_e32 v120, v136, v140
	v_pk_mul_f32 v[70:71], v[156:157], v[70:71]
	v_pk_mul_f32 v[68:69], v[158:159], v[68:69]
	v_add_f32_e32 v74, v74, v75
	v_cvt_pk_bf16_f32 v68, v68, v69
	v_cvt_pk_bf16_f32 v69, v70, v71
	ds_write_b64 v120, v[68:69] offset:2048
	s_nop 1
	s_waitcnt vmcnt(3)
; DI unsigned pk2(float a, float b) { f32x2 v = {a, b}; bf2_t r = __builtin_convertvector(v, bf2_t); return __builtin_bit_cast(unsigned, r); }
;     static DI void run(const f32x4 (&acc)[8][4], const TileCtx& tc, const Params& p, ldsp_t wb) {
;     ...
;             for (int mm = 0; mm < 4; ++mm) { __builtin_amdgcn_sched_barrier(0);
;                 const int m = h * 4 + mm;
;                 const int row = tc.brow + tc.wr * 128 + m * 16 + tc.fr;
;                 float* xr = xrow_ptr(p, row) + col0;
;                 const float* xs = (EK == 1 && tc.l == 0) ? p.x + (size_t)row * DM + col0 : xr;
;                 float part = 0.f;
; #pragma unroll
;                 for (int n = 0; n < 4; ++n) {
;                     f32x4 xv = *(const f32x4*)(xs + n * 16);
;                     xv += gv[n] * acc[m][n];
;                     *(f32x4*)(xr + n * 16) = xv;
;                     if (has_next) {
;                         part += xv[0] * xv[0] + xv[1] * xv[1] + xv[2] * xv[2] + xv[3] * xv[3];
;                         const f32x4 hv = xv * av[n];
;                         u32x2 w; w[0] = pk2(hv[0], hv[1]); w[1] = pk2(hv[2], hv[3]);
;                         wave_put(wb, mm * 16 + tc.fr, n, tc.fq, w);
;                     }
;                 }
;                 if (has_next) {
;                     part += __shfl_xor(part, 16);
;                     part += __shfl_xor(part, 32);
;                     if (tc.fq == 0) ssp[(size_t)row * 16] = part;
;                 }
	v_pk_fma_f32 v[68:69], v[116:117], v[20:21], v[236:237]
	s_nop 0
	v_mul_f32_e32 v75, v69, v69
	v_pk_fma_f32 v[70:71], v[118:119], v[22:23], v[238:239]
	v_fmac_f32_e32 v75, v68, v68
	v_fmac_f32_e32 v75, v70, v70
	global_store_dwordx4 v[130:131], v[68:71], off offset:128
	v_fmac_f32_e32 v75, v71, v71
	v_add_u32_e32 v116, v133, v140
	v_pk_mul_f32 v[70:71], v[152:153], v[70:71]
	v_pk_mul_f32 v[68:69], v[154:155], v[68:69]
	v_add_f32_e32 v74, v74, v75
	v_cvt_pk_bf16_f32 v68, v68, v69
	v_cvt_pk_bf16_f32 v69, v70, v71
	ds_write_b64 v116, v[68:69] offset:2048
	s_nop 1
	v_add_u32_e32 v117, v134, v140
	s_waitcnt vmcnt(3)
	v_pk_fma_f32 v[68:69], v[112:113], v[4:5], v[240:241]
	s_nop 0
	v_mul_f32_e32 v72, v69, v69
	v_pk_fma_f32 v[70:71], v[114:115], v[6:7], v[242:243]
	v_fmac_f32_e32 v72, v68, v68
	v_fmac_f32_e32 v72, v70, v70
	global_store_dwordx4 v[130:131], v[68:71], off offset:192
	v_fmac_f32_e32 v72, v71, v71
	v_add_f32_e32 v72, v74, v72
	v_pk_mul_f32 v[70:71], v[146:147], v[70:71]
	v_pk_mul_f32 v[68:69], v[148:149], v[68:69]
	s_nop 0
	v_cvt_pk_bf16_f32 v68, v68, v69
	v_cvt_pk_bf16_f32 v69, v70, v71
	ds_write_b64 v117, v[68:69] offset:2048
	ds_bpermute_b32 v68, v170, v72
	s_waitcnt lgkmcnt(0)
	v_add_f32_e32 v112, v72, v68
	ds_bpermute_b32 v113, v171, v112
	s_and_saveexec_b64 s[6:7], vcc
	s_cbranch_execz .LBB0_141
	v_lshlrev_b64 v[68:69], 6, v[128:129]
	s_waitcnt lgkmcnt(0)
	v_add_f32_e32 v70, v112, v113
	v_lshl_add_u64 v[68:69], v[144:145], 0, v[68:69]
	global_store_dword v[68:69], v70, off sc1
.LBB0_141:
	s_or_b64 exec, exec, s[6:7]
	v_add_u32_e32 v112, 32, v132
	v_cmp_gt_i32_e64 s[6:7], s33, v112
	v_add_u32_e32 v68, 0xffffc020, v132
	s_waitcnt lgkmcnt(0)
	v_ashrrev_i32_e32 v113, 31, v112
	v_mov_b32_e32 v70, s71
	v_mov_b32_e32 v71, s55
	v_cndmask_b32_e64 v69, 0, v113, s[6:7]
	v_cndmask_b32_e64 v68, v68, v112, s[6:7]
	v_cndmask_b32_e64 v71, v70, v71, s[6:7]
	v_mov_b32_e32 v70, s70
	v_mov_b32_e32 v72, s54
	v_cndmask_b32_e64 v70, v70, v72, s[6:7]
	v_lshlrev_b64 v[68:69], 12, v[68:69]
	v_readlane_b32 s8, v254, 50
	v_lshl_add_u64 v[68:69], v[70:71], 0, v[68:69]
	v_lshlrev_b64 v[70:71], 12, v[112:113]
	v_readlane_b32 s9, v254, 51
	v_lshl_add_u64 v[114:115], v[68:69], 0, v[150:151]
	v_readlane_b32 s10, v254, 52
	v_lshl_add_u64 v[70:71], s[8:9], 0, v[70:71]
	v_cndmask_b32_e64 v69, v69, v71, s[4:5]
	v_cndmask_b32_e64 v68, v68, v70, s[4:5]
	v_lshl_add_u64 v[72:73], v[68:69], 0, v[150:151]
	global_load_dwordx4 v[68:71], v[72:73], off
	global_load_dwordx4 v[232:235], v[72:73], off offset:64
	global_load_dwordx4 v[236:239], v[72:73], off offset:128
	global_load_dwordx4 v[240:243], v[72:73], off offset:192
	v_readlane_b32 s11, v254, 53
	v_readlane_b32 s12, v254, 54
	v_readlane_b32 s13, v254, 55
	v_readlane_b32 s14, v254, 56
	v_readlane_b32 s15, v254, 57
	v_readlane_b32 s16, v254, 58
	v_readlane_b32 s17, v254, 59
	v_readlane_b32 s18, v254, 60
	v_readlane_b32 s19, v254, 61
	v_readlane_b32 s20, v254, 62
	v_readlane_b32 s21, v254, 63
	v_readlane_b32 s22, v255, 0
	v_readlane_b32 s23, v255, 1
	s_waitcnt vmcnt(3)
	v_pk_fma_f32 v[68:69], v[108:109], v[28:29], v[68:69]
	s_nop 0
	v_mul_f32_e32 v74, v69, v69
	v_pk_fma_f32 v[70:71], v[110:111], v[30:31], v[70:71]
	v_fmac_f32_e32 v74, v68, v68
	v_fmac_f32_e32 v74, v70, v70
	global_store_dwordx4 v[114:115], v[68:71], off
	v_fmac_f32_e32 v74, v71, v71
	s_nop 0
	v_pk_mul_f32 v[70:71], v[160:161], v[70:71]
	v_pk_mul_f32 v[68:69], v[162:163], v[68:69]
	s_nop 0
	v_cvt_pk_bf16_f32 v68, v68, v69
	v_cvt_pk_bf16_f32 v69, v70, v71
	ds_write_b64 v124, v[68:69] offset:4096
	s_nop 1
	s_waitcnt vmcnt(3)
	v_pk_fma_f32 v[68:69], v[104:105], v[24:25], v[232:233]
	s_nop 0
	v_mul_f32_e32 v75, v69, v69
	v_pk_fma_f32 v[70:71], v[106:107], v[26:27], v[234:235]
	v_fmac_f32_e32 v75, v68, v68
	v_fmac_f32_e32 v75, v70, v70
	global_store_dwordx4 v[114:115], v[68:71], off offset:64
	v_fmac_f32_e32 v75, v71, v71
	v_add_f32_e32 v74, v74, v75
	v_pk_mul_f32 v[70:71], v[156:157], v[70:71]
	v_pk_mul_f32 v[68:69], v[158:159], v[68:69]
	s_nop 0
	v_cvt_pk_bf16_f32 v68, v68, v69
	v_cvt_pk_bf16_f32 v69, v70, v71
	ds_write_b64 v120, v[68:69] offset:4096
	s_nop 1
	s_waitcnt vmcnt(3)
	v_pk_fma_f32 v[68:69], v[100:101], v[20:21], v[236:237]
	s_nop 0
	v_mul_f32_e32 v75, v69, v69
	v_pk_fma_f32 v[70:71], v[102:103], v[22:23], v[238:239]
	v_fmac_f32_e32 v75, v68, v68
	v_fmac_f32_e32 v75, v70, v70
	global_store_dwordx4 v[114:115], v[68:71], off offset:128
	v_fmac_f32_e32 v75, v71, v71
	v_add_f32_e32 v74, v74, v75
	v_pk_mul_f32 v[70:71], v[152:153], v[70:71]
	v_pk_mul_f32 v[68:69], v[154:155], v[68:69]
	s_nop 0
	v_cvt_pk_bf16_f32 v68, v68, v69
	v_cvt_pk_bf16_f32 v69, v70, v71
	ds_write_b64 v116, v[68:69] offset:4096
	s_nop 1
	s_waitcnt vmcnt(3)
	v_pk_fma_f32 v[68:69], v[96:97], v[4:5], v[240:241]
	s_nop 0
	v_mul_f32_e32 v72, v69, v69
	v_pk_fma_f32 v[70:71], v[98:99], v[6:7], v[242:243]
	v_fmac_f32_e32 v72, v68, v68
	v_fmac_f32_e32 v72, v70, v70
	global_store_dwordx4 v[114:115], v[68:71], off offset:192
	v_fmac_f32_e32 v72, v71, v71
	v_add_f32_e32 v72, v74, v72
	v_pk_mul_f32 v[70:71], v[146:147], v[70:71]
	v_pk_mul_f32 v[68:69], v[148:149], v[68:69]
	s_nop 0
	v_cvt_pk_bf16_f32 v68, v68, v69
	v_cvt_pk_bf16_f32 v69, v70, v71
	ds_write_b64 v117, v[68:69] offset:4096
	ds_bpermute_b32 v68, v170, v72
	s_waitcnt lgkmcnt(0)
	v_add_f32_e32 v96, v72, v68
	ds_bpermute_b32 v97, v171, v96
	s_and_saveexec_b64 s[6:7], vcc
	s_cbranch_execz .LBB0_143
	v_lshlrev_b64 v[68:69], 6, v[112:113]
	s_waitcnt lgkmcnt(0)
	v_add_f32_e32 v70, v96, v97
	v_lshl_add_u64 v[68:69], v[144:145], 0, v[68:69]
	global_store_dword v[68:69], v70, off sc1
; DI unsigned pk2(float a, float b) { f32x2 v = {a, b}; bf2_t r = __builtin_convertvector(v, bf2_t); return __builtin_bit_cast(unsigned, r); }
;     static DI void run(const f32x4 (&acc)[8][4], const TileCtx& tc, const Params& p, ldsp_t wb) {
;     ...
;             for (int mm = 0; mm < 4; ++mm) { __builtin_amdgcn_sched_barrier(0);
;                 const int m = h * 4 + mm;
;                 const int row = tc.brow + tc.wr * 128 + m * 16 + tc.fr;
;                 float* xr = xrow_ptr(p, row) + col0;
;                 const float* xs = (EK == 1 && tc.l == 0) ? p.x + (size_t)row * DM + col0 : xr;
;                 float part = 0.f;
; #pragma unroll
;                 for (int n = 0; n < 4; ++n) {
;                     f32x4 xv = *(const f32x4*)(xs + n * 16);
;                     xv += gv[n] * acc[m][n];
;                     *(f32x4*)(xr + n * 16) = xv;
;                     if (has_next) {
;                         part += xv[0] * xv[0] + xv[1] * xv[1] + xv[2] * xv[2] + xv[3] * xv[3];
;                         const f32x4 hv = xv * av[n];
;                         u32x2 w; w[0] = pk2(hv[0], hv[1]); w[1] = pk2(hv[2], hv[3]);
;                         wave_put(wb, mm * 16 + tc.fr, n, tc.fq, w);
;                     }
;                 }
;                 if (has_next) {
;                     part += __shfl_xor(part, 16);
;                     part += __shfl_xor(part, 32);
;                     if (tc.fq == 0) ssp[(size_t)row * 16] = part;
;                 }
;             }
;             if (has_next) wave_rows_store(wb, tc.lane, p.H + (size_t)(tc.brow + tc.wr * 128 + h * 64) * DM + tc.bcol + tc.wc * 64, DM);
.LBB0_143:
	s_or_b64 exec, exec, s[6:7]
	v_add_u32_e32 v96, 48, v132
	v_cmp_gt_i32_e64 s[6:7], s33, v96
	v_add_u32_e32 v68, 0xffffc030, v132
	s_waitcnt lgkmcnt(0)
	v_ashrrev_i32_e32 v97, 31, v96
	v_mov_b32_e32 v70, s71
	v_mov_b32_e32 v71, s55
	v_cndmask_b32_e64 v69, 0, v97, s[6:7]
	v_cndmask_b32_e64 v68, v68, v96, s[6:7]
	v_cndmask_b32_e64 v71, v70, v71, s[6:7]
	v_mov_b32_e32 v70, s70
	v_mov_b32_e32 v72, s54
	v_cndmask_b32_e64 v70, v70, v72, s[6:7]
	v_lshlrev_b64 v[68:69], 12, v[68:69]
	v_readlane_b32 s8, v254, 50
	v_lshl_add_u64 v[68:69], v[70:71], 0, v[68:69]
	v_lshlrev_b64 v[70:71], 12, v[96:97]
	v_readlane_b32 s9, v254, 51
	v_lshl_add_u64 v[98:99], v[68:69], 0, v[150:151]
	v_readlane_b32 s10, v254, 52
	v_lshl_add_u64 v[70:71], s[8:9], 0, v[70:71]
	v_cndmask_b32_e64 v69, v69, v71, s[4:5]
	v_cndmask_b32_e64 v68, v68, v70, s[4:5]
	v_lshl_add_u64 v[72:73], v[68:69], 0, v[150:151]
	global_load_dwordx4 v[68:71], v[72:73], off
	global_load_dwordx4 v[232:235], v[72:73], off offset:64
	global_load_dwordx4 v[236:239], v[72:73], off offset:128
	global_load_dwordx4 v[240:243], v[72:73], off offset:192
	v_readlane_b32 s11, v254, 53
	v_readlane_b32 s12, v254, 54
	v_readlane_b32 s13, v254, 55
	v_readlane_b32 s14, v254, 56
	v_readlane_b32 s15, v254, 57
	v_readlane_b32 s16, v254, 58
	v_readlane_b32 s17, v254, 59
	v_readlane_b32 s18, v254, 60
	v_readlane_b32 s19, v254, 61
	v_readlane_b32 s20, v254, 62
	v_readlane_b32 s21, v254, 63
	v_readlane_b32 s22, v255, 0
	v_readlane_b32 s23, v255, 1
	s_waitcnt vmcnt(3)
	v_pk_fma_f32 v[68:69], v[92:93], v[28:29], v[68:69]
	s_nop 0
	v_mul_f32_e32 v74, v69, v69
	v_pk_fma_f32 v[70:71], v[94:95], v[30:31], v[70:71]
	v_fmac_f32_e32 v74, v68, v68
	v_fmac_f32_e32 v74, v70, v70
	global_store_dwordx4 v[98:99], v[68:71], off
	v_fmac_f32_e32 v74, v71, v71
	s_nop 0
	v_pk_mul_f32 v[70:71], v[160:161], v[70:71]
	v_pk_mul_f32 v[68:69], v[162:163], v[68:69]
	s_nop 0
	v_cvt_pk_bf16_f32 v68, v68, v69
	v_cvt_pk_bf16_f32 v69, v70, v71
	ds_write_b64 v124, v[68:69] offset:6144
	s_nop 1
	s_waitcnt vmcnt(3)
	v_pk_fma_f32 v[68:69], v[88:89], v[24:25], v[232:233]
	s_nop 0
	v_mul_f32_e32 v75, v69, v69
	v_pk_fma_f32 v[70:71], v[90:91], v[26:27], v[234:235]
	v_fmac_f32_e32 v75, v68, v68
	v_fmac_f32_e32 v75, v70, v70
	global_store_dwordx4 v[98:99], v[68:71], off offset:64
	v_fmac_f32_e32 v75, v71, v71
	v_add_f32_e32 v74, v74, v75
	v_pk_mul_f32 v[70:71], v[156:157], v[70:71]
	v_pk_mul_f32 v[68:69], v[158:159], v[68:69]
	s_nop 0
	v_cvt_pk_bf16_f32 v68, v68, v69
	v_cvt_pk_bf16_f32 v69, v70, v71
	ds_write_b64 v120, v[68:69] offset:6144
	s_nop 1
	s_waitcnt vmcnt(3)
	v_pk_fma_f32 v[68:69], v[84:85], v[20:21], v[236:237]
	s_nop 0
	v_mul_f32_e32 v75, v69, v69
	v_pk_fma_f32 v[70:71], v[86:87], v[22:23], v[238:239]
	v_fmac_f32_e32 v75, v68, v68
	v_fmac_f32_e32 v75, v70, v70
	global_store_dwordx4 v[98:99], v[68:71], off offset:128
	v_fmac_f32_e32 v75, v71, v71
	v_add_f32_e32 v74, v74, v75
	v_pk_mul_f32 v[70:71], v[152:153], v[70:71]
	v_pk_mul_f32 v[68:69], v[154:155], v[68:69]
	s_nop 0
	v_cvt_pk_bf16_f32 v68, v68, v69
	v_cvt_pk_bf16_f32 v69, v70, v71
	ds_write_b64 v116, v[68:69] offset:6144
	s_nop 1
	s_waitcnt vmcnt(3)
	v_pk_fma_f32 v[68:69], v[80:81], v[4:5], v[240:241]
	s_nop 0
	v_mul_f32_e32 v72, v69, v69
	v_pk_fma_f32 v[70:71], v[82:83], v[6:7], v[242:243]
	v_fmac_f32_e32 v72, v68, v68
	v_fmac_f32_e32 v72, v70, v70
	global_store_dwordx4 v[98:99], v[68:71], off offset:192
	v_fmac_f32_e32 v72, v71, v71
	v_add_f32_e32 v72, v74, v72
	v_pk_mul_f32 v[70:71], v[146:147], v[70:71]
	v_pk_mul_f32 v[68:69], v[148:149], v[68:69]
	s_nop 0
	v_cvt_pk_bf16_f32 v68, v68, v69
	v_cvt_pk_bf16_f32 v69, v70, v71
	ds_write_b64 v117, v[68:69] offset:6144
	ds_bpermute_b32 v68, v170, v72
	s_waitcnt lgkmcnt(0)
	v_add_f32_e32 v80, v72, v68
	ds_bpermute_b32 v81, v171, v80
	s_and_saveexec_b64 s[6:7], vcc
	s_cbranch_execz .LBB0_145
	v_lshlrev_b64 v[68:69], 6, v[96:97]
	s_waitcnt lgkmcnt(0)
	v_add_f32_e32 v70, v80, v81
	v_lshl_add_u64 v[68:69], v[144:145], 0, v[68:69]
	global_store_dword v[68:69], v70, off sc1
.LBB0_145:
	s_or_b64 exec, exec, s[6:7]
	v_lshrrev_b32_e32 v80, 3, v175
	v_xor_b32_e32 v70, v80, v175
	v_ashrrev_i32_e32 v165, 31, v164
	v_lshlrev_b32_e32 v70, 4, v70
	v_lshlrev_b64 v[68:69], 11, v[164:165]
	v_and_b32_e32 v70, 0x70, v70
	v_lshl_add_u64 v[68:69], s[82:83], 0, v[68:69]
	s_ashr_i32 s39, s38, 31
	s_waitcnt lgkmcnt(0)
	v_add_u32_e32 v81, v176, v70
	v_lshlrev_b32_e32 v70, 3, v175
	v_lshl_add_u64 v[68:69], s[38:39], 1, v[68:69]
	v_lshlrev_b32_e32 v88, 1, v172
	v_mov_b32_e32 v89, v193
	v_and_b32_e32 v70, 56, v70
	v_lshl_add_u64 v[68:69], v[68:69], 0, v[88:89]
	v_lshlrev_b32_e32 v96, 1, v70
	v_mov_b32_e32 v97, v193
	v_lshl_add_u64 v[72:73], v[68:69], 0, v[96:97]
	v_lshlrev_b32_e32 v68, 7, v80
	v_add_u32_e32 v111, v81, v68
	ds_read_b128 v[68:71], v111
	v_lshlrev_b32_e32 v192, 11, v80
	v_lshl_add_u64 v[74:75], v[72:73], 0, v[192:193]
	v_mov_b32_e32 v95, v193
	v_mov_b32_e32 v93, v193
	s_waitcnt lgkmcnt(0)
	global_store_dwordx4 v[74:75], v[68:71], off sc1
	v_or_b32_e32 v74, 8, v80
	v_lshlrev_b32_e32 v94, 11, v74
	v_lshlrev_b32_e32 v68, 7, v74
	v_add_u32_e32 v110, v81, v68
	ds_read_b128 v[68:71], v110
	v_lshl_add_u64 v[74:75], v[72:73], 0, v[94:95]
	v_mov_b32_e32 v91, v193
	v_mov_b32_e32 v83, v193
	v_mov_b32_e32 v87, v193
	s_waitcnt lgkmcnt(0)
	global_store_dwordx4 v[74:75], v[68:71], off sc1
	v_or_b32_e32 v74, 16, v80
	v_lshlrev_b32_e32 v92, 11, v74
	v_lshlrev_b32_e32 v68, 7, v74
	v_add_u32_e32 v109, v81, v68
	ds_read_b128 v[68:71], v109
	v_lshl_add_u64 v[74:75], v[72:73], 0, v[92:93]
	v_mov_b32_e32 v85, v193
	s_waitcnt lgkmcnt(0)
; DI unsigned pk2(float a, float b) { f32x2 v = {a, b}; bf2_t r = __builtin_convertvector(v, bf2_t); return __builtin_bit_cast(unsigned, r); }
;     static DI void run(const f32x4 (&acc)[8][4], const TileCtx& tc, const Params& p, ldsp_t wb) {
;     ...
;             for (int mm = 0; mm < 4; ++mm) { __builtin_amdgcn_sched_barrier(0);
;                 const int m = h * 4 + mm;
;                 const int row = tc.brow + tc.wr * 128 + m * 16 + tc.fr;
;                 float* xr = xrow_ptr(p, row) + col0;
;                 const float* xs = (EK == 1 && tc.l == 0) ? p.x + (size_t)row * DM + col0 : xr;
;                 float part = 0.f;
; #pragma unroll
;                 for (int n = 0; n < 4; ++n) {
;                     f32x4 xv = *(const f32x4*)(xs + n * 16);
;                     xv += gv[n] * acc[m][n];
;                     *(f32x4*)(xr + n * 16) = xv;
;                     if (has_next) {
;                         part += xv[0] * xv[0] + xv[1] * xv[1] + xv[2] * xv[2] + xv[3] * xv[3];
;                         const f32x4 hv = xv * av[n];
;                         u32x2 w; w[0] = pk2(hv[0], hv[1]); w[1] = pk2(hv[2], hv[3]);
;                         wave_put(wb, mm * 16 + tc.fr, n, tc.fq, w);
;                     }
;                 }
;                 if (has_next) {
;                     part += __shfl_xor(part, 16);
;                     part += __shfl_xor(part, 32);
;                     if (tc.fq == 0) ssp[(size_t)row * 16] = part;
;                 }
;             }
;             if (has_next) wave_rows_store(wb, tc.lane, p.H + (size_t)(tc.brow + tc.wr * 128 + h * 64) * DM + tc.bcol + tc.wc * 64, DM);
	global_store_dwordx4 v[74:75], v[68:71], off sc1
	v_or_b32_e32 v74, 24, v80
	s_nop 0
	v_lshlrev_b32_e32 v68, 7, v74
	v_add_u32_e32 v108, v81, v68
	ds_read_b128 v[68:71], v108
	v_lshlrev_b32_e32 v90, 11, v74
	v_lshl_add_u64 v[74:75], v[72:73], 0, v[90:91]
	s_waitcnt lgkmcnt(0)
	global_store_dwordx4 v[74:75], v[68:71], off sc1
	v_or_b32_e32 v74, 32, v80
	s_nop 0
	v_lshlrev_b32_e32 v68, 7, v74
	v_add_u32_e32 v104, v81, v68
	ds_read_b128 v[68:71], v104
	v_lshlrev_b32_e32 v82, 11, v74
	v_lshl_add_u64 v[74:75], v[72:73], 0, v[82:83]
	s_waitcnt lgkmcnt(0)
	global_store_dwordx4 v[74:75], v[68:71], off sc1
	v_or_b32_e32 v74, 40, v80
	s_nop 0
	v_lshlrev_b32_e32 v68, 7, v74
	v_add_u32_e32 v105, v81, v68
	ds_read_b128 v[68:71], v105
	v_lshlrev_b32_e32 v86, 11, v74
	v_lshl_add_u64 v[74:75], v[72:73], 0, v[86:87]
	s_waitcnt lgkmcnt(0)
	global_store_dwordx4 v[74:75], v[68:71], off sc1
	v_or_b32_e32 v74, 48, v80
	s_nop 0
	v_lshlrev_b32_e32 v68, 7, v74
	v_add_u32_e32 v106, v81, v68
	ds_read_b128 v[68:71], v106
	v_lshlrev_b32_e32 v84, 11, v74
	v_lshl_add_u64 v[74:75], v[72:73], 0, v[84:85]
	s_waitcnt lgkmcnt(0)
	global_store_dwordx4 v[74:75], v[68:71], off sc1
	v_or_b32_e32 v74, 56, v80
	s_nop 0
	v_lshlrev_b32_e32 v68, 7, v74
	v_add_u32_e32 v107, v81, v68
	ds_read_b128 v[68:71], v107
	v_lshlrev_b32_e32 v80, 11, v74
	v_mov_b32_e32 v81, v193
	v_lshl_add_u64 v[72:73], v[72:73], 0, v[80:81]
	s_waitcnt lgkmcnt(0)
	global_store_dwordx4 v[72:73], v[68:71], off sc1
	v_add3_u32 v98, v174, s41, 64
	v_or_b32_e32 v100, v98, v173
	v_cmp_gt_i32_e64 s[6:7], s33, v100
	v_add_u32_e32 v68, 0xffffc000, v100
	v_ashrrev_i32_e32 v101, 31, v100
	v_mov_b32_e32 v70, s71
	v_mov_b32_e32 v71, s55
	v_cndmask_b32_e64 v69, 0, v101, s[6:7]
	v_cndmask_b32_e64 v68, v68, v100, s[6:7]
	v_cndmask_b32_e64 v71, v70, v71, s[6:7]
	v_mov_b32_e32 v70, s70
	v_mov_b32_e32 v72, s54
	v_cndmask_b32_e64 v70, v70, v72, s[6:7]
	v_lshlrev_b64 v[68:69], 12, v[68:69]
	v_readlane_b32 s8, v254, 50
	v_lshl_add_u64 v[68:69], v[70:71], 0, v[68:69]
	v_lshlrev_b64 v[70:71], 12, v[100:101]
	v_readlane_b32 s9, v254, 51
	v_lshl_add_u64 v[102:103], v[68:69], 0, v[150:151]
	v_readlane_b32 s10, v254, 52
	v_lshl_add_u64 v[70:71], s[8:9], 0, v[70:71]
	v_cndmask_b32_e64 v69, v69, v71, s[4:5]
	v_cndmask_b32_e64 v68, v68, v70, s[4:5]
	v_lshl_add_u64 v[72:73], v[68:69], 0, v[150:151]
	global_load_dwordx4 v[68:71], v[72:73], off
	global_load_dwordx4 v[232:235], v[72:73], off offset:64
	global_load_dwordx4 v[236:239], v[72:73], off offset:128
	global_load_dwordx4 v[240:243], v[72:73], off offset:192
	v_readlane_b32 s11, v254, 53
	v_readlane_b32 s12, v254, 54
	v_readlane_b32 s13, v254, 55
	v_readlane_b32 s14, v254, 56
	v_readlane_b32 s15, v254, 57
	v_readlane_b32 s16, v254, 58
	v_readlane_b32 s17, v254, 59
	v_readlane_b32 s18, v254, 60
	v_readlane_b32 s19, v254, 61
	v_readlane_b32 s20, v254, 62
	v_readlane_b32 s21, v254, 63
	v_readlane_b32 s22, v255, 0
	v_readlane_b32 s23, v255, 1
	s_waitcnt vmcnt(3)
	v_pk_fma_f32 v[68:69], v[76:77], v[28:29], v[68:69]
	s_nop 0
	v_mul_f32_e32 v74, v69, v69
	v_pk_fma_f32 v[70:71], v[78:79], v[30:31], v[70:71]
	v_fmac_f32_e32 v74, v68, v68
	v_fmac_f32_e32 v74, v70, v70
	global_store_dwordx4 v[102:103], v[68:71], off
	v_fmac_f32_e32 v74, v71, v71
	s_nop 0
	v_pk_mul_f32 v[70:71], v[160:161], v[70:71]
	v_pk_mul_f32 v[68:69], v[162:163], v[68:69]
	s_nop 0
	v_cvt_pk_bf16_f32 v68, v68, v69
	v_cvt_pk_bf16_f32 v69, v70, v71
	ds_write_b64 v124, v[68:69]
	s_nop 1
	s_waitcnt vmcnt(3)
	v_pk_fma_f32 v[68:69], v[198:199], v[24:25], v[232:233]
	s_nop 0
	v_mul_f32_e32 v75, v69, v69
	v_pk_fma_f32 v[70:71], v[200:201], v[26:27], v[234:235]
	v_fmac_f32_e32 v75, v68, v68
	v_fmac_f32_e32 v75, v70, v70
	global_store_dwordx4 v[102:103], v[68:71], off offset:64
	v_fmac_f32_e32 v75, v71, v71
	v_add_f32_e32 v74, v74, v75
	v_pk_mul_f32 v[70:71], v[156:157], v[70:71]
	v_pk_mul_f32 v[68:69], v[158:159], v[68:69]
	s_nop 0
	v_cvt_pk_bf16_f32 v68, v68, v69
	v_cvt_pk_bf16_f32 v69, v70, v71
	ds_write_b64 v120, v[68:69]
	s_nop 1
	s_waitcnt vmcnt(3)
	v_pk_fma_f32 v[68:69], v[194:195], v[20:21], v[236:237]
	s_nop 0
	v_mul_f32_e32 v75, v69, v69
	v_pk_fma_f32 v[70:71], v[196:197], v[22:23], v[238:239]
	v_fmac_f32_e32 v75, v68, v68
	v_fmac_f32_e32 v75, v70, v70
	global_store_dwordx4 v[102:103], v[68:71], off offset:128
	v_fmac_f32_e32 v75, v71, v71
	v_add_f32_e32 v74, v74, v75
	v_pk_mul_f32 v[70:71], v[152:153], v[70:71]
	v_pk_mul_f32 v[68:69], v[154:155], v[68:69]
	s_nop 0
	v_cvt_pk_bf16_f32 v68, v68, v69
	v_cvt_pk_bf16_f32 v69, v70, v71
	ds_write_b64 v116, v[68:69]
	s_nop 1
	s_waitcnt vmcnt(3)
	v_pk_fma_f32 v[64:65], v[64:65], v[4:5], v[240:241]
	s_nop 0
	v_mul_f32_e32 v68, v65, v65
	v_pk_fma_f32 v[66:67], v[66:67], v[6:7], v[242:243]
	v_fmac_f32_e32 v68, v64, v64
	v_fmac_f32_e32 v68, v66, v66
	global_store_dwordx4 v[102:103], v[64:67], off offset:192
	v_fmac_f32_e32 v68, v67, v67
	v_add_f32_e32 v68, v74, v68
	v_pk_mul_f32 v[66:67], v[146:147], v[66:67]
	v_pk_mul_f32 v[64:65], v[148:149], v[64:65]
	s_nop 0
	v_cvt_pk_bf16_f32 v64, v64, v65
	v_cvt_pk_bf16_f32 v65, v66, v67
	ds_write_b64 v117, v[64:65]
	ds_bpermute_b32 v64, v170, v68
	s_waitcnt lgkmcnt(0)
	v_add_f32_e32 v64, v68, v64
	ds_bpermute_b32 v65, v171, v64
	s_and_saveexec_b64 s[6:7], vcc
	s_cbranch_execz .LBB0_147
	s_waitcnt lgkmcnt(0)
	v_add_f32_e32 v66, v64, v65
	v_lshlrev_b64 v[64:65], 6, v[100:101]
	v_lshl_add_u64 v[64:65], v[144:145], 0, v[64:65]
	global_store_dword v[64:65], v66, off sc1
; DI unsigned pk2(float a, float b) { f32x2 v = {a, b}; bf2_t r = __builtin_convertvector(v, bf2_t); return __builtin_bit_cast(unsigned, r); }
;     static DI void run(const f32x4 (&acc)[8][4], const TileCtx& tc, const Params& p, ldsp_t wb) {
;     ...
;             for (int mm = 0; mm < 4; ++mm) { __builtin_amdgcn_sched_barrier(0);
;                 const int m = h * 4 + mm;
;                 const int row = tc.brow + tc.wr * 128 + m * 16 + tc.fr;
;                 float* xr = xrow_ptr(p, row) + col0;
;                 const float* xs = (EK == 1 && tc.l == 0) ? p.x + (size_t)row * DM + col0 : xr;
;                 float part = 0.f;
; #pragma unroll
;                 for (int n = 0; n < 4; ++n) {
;                     f32x4 xv = *(const f32x4*)(xs + n * 16);
;                     xv += gv[n] * acc[m][n];
;                     *(f32x4*)(xr + n * 16) = xv;
;                     if (has_next) {
;                         part += xv[0] * xv[0] + xv[1] * xv[1] + xv[2] * xv[2] + xv[3] * xv[3];
;                         const f32x4 hv = xv * av[n];
;                         u32x2 w; w[0] = pk2(hv[0], hv[1]); w[1] = pk2(hv[2], hv[3]);
;                         wave_put(wb, mm * 16 + tc.fr, n, tc.fq, w);
;                     }
;                 }
;                 if (has_next) {
;                     part += __shfl_xor(part, 16);
;                     part += __shfl_xor(part, 32);
;                     if (tc.fq == 0) ssp[(size_t)row * 16] = part;
;                 }
.LBB0_147:
	s_or_b64 exec, exec, s[6:7]
	v_add_u32_e32 v64, 0x50, v132
	v_cmp_gt_i32_e64 s[6:7], s33, v64
	v_add_u32_e32 v66, 0xffffc050, v132
	s_waitcnt lgkmcnt(0)
	v_ashrrev_i32_e32 v65, 31, v64
	v_mov_b32_e32 v68, s71
	v_mov_b32_e32 v69, s55
	v_cndmask_b32_e64 v67, 0, v65, s[6:7]
	v_cndmask_b32_e64 v66, v66, v64, s[6:7]
	v_cndmask_b32_e64 v69, v68, v69, s[6:7]
	v_mov_b32_e32 v68, s70
	v_mov_b32_e32 v70, s54
	v_readlane_b32 s8, v254, 50
	v_cndmask_b32_e64 v68, v68, v70, s[6:7]
	v_lshlrev_b64 v[66:67], 12, v[66:67]
	v_lshlrev_b64 v[70:71], 12, v[64:65]
	v_readlane_b32 s9, v254, 51
	v_lshl_add_u64 v[68:69], v[68:69], 0, v[66:67]
	v_lshl_add_u64 v[66:67], v[68:69], 0, v[150:151]
	v_lshl_add_u64 v[70:71], s[8:9], 0, v[70:71]
	v_cndmask_b32_e64 v69, v69, v71, s[4:5]
	v_cndmask_b32_e64 v68, v68, v70, s[4:5]
	v_lshl_add_u64 v[72:73], v[68:69], 0, v[150:151]
	global_load_dwordx4 v[68:71], v[72:73], off
	global_load_dwordx4 v[232:235], v[72:73], off offset:64
	global_load_dwordx4 v[236:239], v[72:73], off offset:128
	global_load_dwordx4 v[240:243], v[72:73], off offset:192
	v_readlane_b32 s10, v254, 52
	v_readlane_b32 s11, v254, 53
	v_readlane_b32 s12, v254, 54
	v_readlane_b32 s13, v254, 55
	v_readlane_b32 s14, v254, 56
	v_readlane_b32 s15, v254, 57
	v_readlane_b32 s16, v254, 58
	v_readlane_b32 s17, v254, 59
	v_readlane_b32 s18, v254, 60
	v_readlane_b32 s19, v254, 61
	v_readlane_b32 s20, v254, 62
	v_readlane_b32 s21, v254, 63
	v_readlane_b32 s22, v255, 0
	v_readlane_b32 s23, v255, 1
	s_waitcnt vmcnt(3)
	v_pk_fma_f32 v[60:61], v[60:61], v[28:29], v[68:69]
	s_nop 0
	v_mul_f32_e32 v68, v61, v61
	v_pk_fma_f32 v[62:63], v[62:63], v[30:31], v[70:71]
	v_fmac_f32_e32 v68, v60, v60
	v_fmac_f32_e32 v68, v62, v62
	global_store_dwordx4 v[66:67], v[60:63], off
	v_fmac_f32_e32 v68, v63, v63
	s_nop 0
	v_pk_mul_f32 v[62:63], v[160:161], v[62:63]
	v_pk_mul_f32 v[60:61], v[162:163], v[60:61]
	s_nop 0
	v_cvt_pk_bf16_f32 v60, v60, v61
	v_cvt_pk_bf16_f32 v61, v62, v63
	ds_write_b64 v124, v[60:61] offset:2048
	s_nop 1
	s_waitcnt vmcnt(3)
	v_pk_fma_f32 v[56:57], v[56:57], v[24:25], v[232:233]
	s_nop 0
	v_mul_f32_e32 v60, v57, v57
	v_pk_fma_f32 v[58:59], v[58:59], v[26:27], v[234:235]
	v_fmac_f32_e32 v60, v56, v56
	v_fmac_f32_e32 v60, v58, v58
	global_store_dwordx4 v[66:67], v[56:59], off offset:64
	v_fmac_f32_e32 v60, v59, v59
	v_add_f32_e32 v60, v68, v60
	v_pk_mul_f32 v[58:59], v[156:157], v[58:59]
	v_pk_mul_f32 v[56:57], v[158:159], v[56:57]
	s_nop 0
	v_cvt_pk_bf16_f32 v56, v56, v57
	v_cvt_pk_bf16_f32 v57, v58, v59
	ds_write_b64 v120, v[56:57] offset:2048
	s_nop 1
	s_waitcnt vmcnt(3)
	v_pk_fma_f32 v[52:53], v[52:53], v[20:21], v[236:237]
	s_nop 0
	v_mul_f32_e32 v56, v53, v53
	v_pk_fma_f32 v[54:55], v[54:55], v[22:23], v[238:239]
	v_fmac_f32_e32 v56, v52, v52
	v_fmac_f32_e32 v56, v54, v54
	global_store_dwordx4 v[66:67], v[52:55], off offset:128
	v_fmac_f32_e32 v56, v55, v55
	v_add_f32_e32 v56, v60, v56
	v_pk_mul_f32 v[54:55], v[152:153], v[54:55]
	v_pk_mul_f32 v[52:53], v[154:155], v[52:53]
	s_nop 0
	v_cvt_pk_bf16_f32 v52, v52, v53
	v_cvt_pk_bf16_f32 v53, v54, v55
	ds_write_b64 v116, v[52:53] offset:2048
	s_nop 1
	s_waitcnt vmcnt(3)
	v_pk_fma_f32 v[48:49], v[48:49], v[4:5], v[240:241]
	s_nop 0
	v_mul_f32_e32 v52, v49, v49
	v_pk_fma_f32 v[50:51], v[50:51], v[6:7], v[242:243]
	v_fmac_f32_e32 v52, v48, v48
	v_fmac_f32_e32 v52, v50, v50
	global_store_dwordx4 v[66:67], v[48:51], off offset:192
	v_fmac_f32_e32 v52, v51, v51
	v_add_f32_e32 v52, v56, v52
	v_pk_mul_f32 v[50:51], v[146:147], v[50:51]
	v_pk_mul_f32 v[48:49], v[148:149], v[48:49]
	s_nop 0
	v_cvt_pk_bf16_f32 v48, v48, v49
	v_cvt_pk_bf16_f32 v49, v50, v51
	ds_write_b64 v117, v[48:49] offset:2048
	ds_bpermute_b32 v48, v170, v52
	s_waitcnt lgkmcnt(0)
	v_add_f32_e32 v48, v52, v48
	ds_bpermute_b32 v49, v171, v48
	s_and_saveexec_b64 s[6:7], vcc
	s_cbranch_execz .LBB0_149
	s_waitcnt lgkmcnt(0)
	v_add_f32_e32 v50, v48, v49
	v_lshlrev_b64 v[48:49], 6, v[64:65]
	v_lshl_add_u64 v[48:49], v[144:145], 0, v[48:49]
	global_store_dword v[48:49], v50, off sc1
.LBB0_149:
	s_or_b64 exec, exec, s[6:7]
	v_add_u32_e32 v48, 0x60, v132
	v_cmp_gt_i32_e64 s[6:7], s33, v48
	v_add_u32_e32 v50, 0xffffc060, v132
	s_waitcnt lgkmcnt(0)
	v_ashrrev_i32_e32 v49, 31, v48
	v_mov_b32_e32 v52, s71
	v_mov_b32_e32 v53, s55
	v_cndmask_b32_e64 v51, 0, v49, s[6:7]
	v_cndmask_b32_e64 v50, v50, v48, s[6:7]
	v_cndmask_b32_e64 v53, v52, v53, s[6:7]
	v_mov_b32_e32 v52, s70
	v_mov_b32_e32 v54, s54
	v_readlane_b32 s8, v254, 50
	v_cndmask_b32_e64 v52, v52, v54, s[6:7]
	v_lshlrev_b64 v[50:51], 12, v[50:51]
	v_lshlrev_b64 v[54:55], 12, v[48:49]
	v_readlane_b32 s9, v254, 51
	v_lshl_add_u64 v[52:53], v[52:53], 0, v[50:51]
	v_lshl_add_u64 v[50:51], v[52:53], 0, v[150:151]
	v_lshl_add_u64 v[54:55], s[8:9], 0, v[54:55]
	v_cndmask_b32_e64 v53, v53, v55, s[4:5]
	v_cndmask_b32_e64 v52, v52, v54, s[4:5]
	v_lshl_add_u64 v[56:57], v[52:53], 0, v[150:151]
	global_load_dwordx4 v[52:55], v[56:57], off
	global_load_dwordx4 v[232:235], v[56:57], off offset:64
	global_load_dwordx4 v[236:239], v[56:57], off offset:128
	global_load_dwordx4 v[240:243], v[56:57], off offset:192
	v_readlane_b32 s10, v254, 52
	v_readlane_b32 s11, v254, 53
	v_readlane_b32 s12, v254, 54
	v_readlane_b32 s13, v254, 55
	v_readlane_b32 s14, v254, 56
	v_readlane_b32 s15, v254, 57
	v_readlane_b32 s16, v254, 58
	v_readlane_b32 s17, v254, 59
	v_readlane_b32 s18, v254, 60
	v_readlane_b32 s19, v254, 61
	v_readlane_b32 s20, v254, 62
	v_readlane_b32 s21, v254, 63
	v_readlane_b32 s22, v255, 0
	v_readlane_b32 s23, v255, 1
	s_waitcnt vmcnt(3)
; DI unsigned pk2(float a, float b) { f32x2 v = {a, b}; bf2_t r = __builtin_convertvector(v, bf2_t); return __builtin_bit_cast(unsigned, r); }
;     static DI void run(const f32x4 (&acc)[8][4], const TileCtx& tc, const Params& p, ldsp_t wb) {
;     ...
;             for (int mm = 0; mm < 4; ++mm) { __builtin_amdgcn_sched_barrier(0);
;                 const int m = h * 4 + mm;
;                 const int row = tc.brow + tc.wr * 128 + m * 16 + tc.fr;
;                 float* xr = xrow_ptr(p, row) + col0;
;                 const float* xs = (EK == 1 && tc.l == 0) ? p.x + (size_t)row * DM + col0 : xr;
;                 float part = 0.f;
; #pragma unroll
;                 for (int n = 0; n < 4; ++n) {
;                     f32x4 xv = *(const f32x4*)(xs + n * 16);
;                     xv += gv[n] * acc[m][n];
;                     *(f32x4*)(xr + n * 16) = xv;
;                     if (has_next) {
;                         part += xv[0] * xv[0] + xv[1] * xv[1] + xv[2] * xv[2] + xv[3] * xv[3];
;                         const f32x4 hv = xv * av[n];
;                         u32x2 w; w[0] = pk2(hv[0], hv[1]); w[1] = pk2(hv[2], hv[3]);
;                         wave_put(wb, mm * 16 + tc.fr, n, tc.fq, w);
;                     }
;                 }
;                 if (has_next) {
;                     part += __shfl_xor(part, 16);
;                     part += __shfl_xor(part, 32);
;                     if (tc.fq == 0) ssp[(size_t)row * 16] = part;
;                 }
	v_pk_fma_f32 v[44:45], v[44:45], v[28:29], v[52:53]
	s_nop 0
	v_mul_f32_e32 v52, v45, v45
	v_pk_fma_f32 v[46:47], v[46:47], v[30:31], v[54:55]
	v_fmac_f32_e32 v52, v44, v44
	v_fmac_f32_e32 v52, v46, v46
	global_store_dwordx4 v[50:51], v[44:47], off
	v_fmac_f32_e32 v52, v47, v47
	s_nop 0
	v_pk_mul_f32 v[46:47], v[160:161], v[46:47]
	v_pk_mul_f32 v[44:45], v[162:163], v[44:45]
	s_nop 0
	v_cvt_pk_bf16_f32 v44, v44, v45
	v_cvt_pk_bf16_f32 v45, v46, v47
	ds_write_b64 v124, v[44:45] offset:4096
	s_nop 1
	s_waitcnt vmcnt(3)
	v_pk_fma_f32 v[40:41], v[40:41], v[24:25], v[232:233]
	s_nop 0
	v_mul_f32_e32 v44, v41, v41
	v_pk_fma_f32 v[42:43], v[42:43], v[26:27], v[234:235]
	v_fmac_f32_e32 v44, v40, v40
	v_fmac_f32_e32 v44, v42, v42
	global_store_dwordx4 v[50:51], v[40:43], off offset:64
	v_fmac_f32_e32 v44, v43, v43
	v_add_f32_e32 v44, v52, v44
	v_pk_mul_f32 v[42:43], v[156:157], v[42:43]
	v_pk_mul_f32 v[40:41], v[158:159], v[40:41]
	s_nop 0
	v_cvt_pk_bf16_f32 v40, v40, v41
	v_cvt_pk_bf16_f32 v41, v42, v43
	ds_write_b64 v120, v[40:41] offset:4096
	s_nop 1
	s_waitcnt vmcnt(3)
	v_pk_fma_f32 v[36:37], v[36:37], v[20:21], v[236:237]
	s_nop 0
	v_mul_f32_e32 v40, v37, v37
	v_pk_fma_f32 v[38:39], v[38:39], v[22:23], v[238:239]
	v_fmac_f32_e32 v40, v36, v36
	v_fmac_f32_e32 v40, v38, v38
	global_store_dwordx4 v[50:51], v[36:39], off offset:128
	v_fmac_f32_e32 v40, v39, v39
	v_add_f32_e32 v40, v44, v40
	v_pk_mul_f32 v[38:39], v[152:153], v[38:39]
	v_pk_mul_f32 v[36:37], v[154:155], v[36:37]
	s_nop 0
	v_cvt_pk_bf16_f32 v36, v36, v37
	v_cvt_pk_bf16_f32 v37, v38, v39
	ds_write_b64 v116, v[36:37] offset:4096
	s_nop 1
	s_waitcnt vmcnt(3)
	v_pk_fma_f32 v[32:33], v[32:33], v[4:5], v[240:241]
	s_nop 0
	v_mul_f32_e32 v36, v33, v33
	v_pk_fma_f32 v[34:35], v[34:35], v[6:7], v[242:243]
	v_fmac_f32_e32 v36, v32, v32
	v_fmac_f32_e32 v36, v34, v34
	global_store_dwordx4 v[50:51], v[32:35], off offset:192
	v_fmac_f32_e32 v36, v35, v35
	v_add_f32_e32 v36, v40, v36
	v_pk_mul_f32 v[34:35], v[146:147], v[34:35]
	v_pk_mul_f32 v[32:33], v[148:149], v[32:33]
	s_nop 0
	v_cvt_pk_bf16_f32 v32, v32, v33
	v_cvt_pk_bf16_f32 v33, v34, v35
	ds_write_b64 v117, v[32:33] offset:4096
	ds_bpermute_b32 v32, v170, v36
	s_waitcnt lgkmcnt(0)
	v_add_f32_e32 v32, v36, v32
	ds_bpermute_b32 v33, v171, v32
	s_and_saveexec_b64 s[6:7], vcc
	s_cbranch_execz .LBB0_151
	s_waitcnt lgkmcnt(0)
	v_add_f32_e32 v34, v32, v33
	v_lshlrev_b64 v[32:33], 6, v[48:49]
	v_lshl_add_u64 v[32:33], v[144:145], 0, v[32:33]
	global_store_dword v[32:33], v34, off sc1
.LBB0_151:
	s_or_b64 exec, exec, s[6:7]
	v_add_u32_e32 v32, 0x70, v132
	v_cmp_gt_i32_e64 s[6:7], s33, v32
	v_add_u32_e32 v34, 0xffffc070, v132
	s_waitcnt lgkmcnt(0)
	v_ashrrev_i32_e32 v33, 31, v32
	v_mov_b32_e32 v36, s71
	v_mov_b32_e32 v37, s55
	v_cndmask_b32_e64 v35, 0, v33, s[6:7]
	v_cndmask_b32_e64 v34, v34, v32, s[6:7]
	v_cndmask_b32_e64 v37, v36, v37, s[6:7]
	v_mov_b32_e32 v36, s70
	v_mov_b32_e32 v38, s54
	v_readlane_b32 s8, v254, 50
	v_cndmask_b32_e64 v36, v36, v38, s[6:7]
	v_lshlrev_b64 v[34:35], 12, v[34:35]
	v_lshlrev_b64 v[38:39], 12, v[32:33]
	v_readlane_b32 s9, v254, 51
	v_lshl_add_u64 v[36:37], v[36:37], 0, v[34:35]
	v_lshl_add_u64 v[34:35], v[36:37], 0, v[150:151]
	v_lshl_add_u64 v[38:39], s[8:9], 0, v[38:39]
	v_cndmask_b32_e64 v37, v37, v39, s[4:5]
	v_cndmask_b32_e64 v36, v36, v38, s[4:5]
	v_lshl_add_u64 v[40:41], v[36:37], 0, v[150:151]
	global_load_dwordx4 v[36:39], v[40:41], off
	global_load_dwordx4 v[232:235], v[40:41], off offset:64
	global_load_dwordx4 v[236:239], v[40:41], off offset:128
	global_load_dwordx4 v[240:243], v[40:41], off offset:192
	v_readlane_b32 s10, v254, 52
	v_readlane_b32 s11, v254, 53
	v_readlane_b32 s12, v254, 54
	v_readlane_b32 s13, v254, 55
	v_readlane_b32 s14, v254, 56
	v_readlane_b32 s15, v254, 57
	v_readlane_b32 s16, v254, 58
	v_readlane_b32 s17, v254, 59
	v_readlane_b32 s18, v254, 60
	v_readlane_b32 s19, v254, 61
	v_readlane_b32 s20, v254, 62
	v_readlane_b32 s21, v254, 63
	v_readlane_b32 s22, v255, 0
	v_readlane_b32 s23, v255, 1
	s_waitcnt vmcnt(3)
	v_pk_fma_f32 v[16:17], v[16:17], v[28:29], v[36:37]
	s_nop 0
	v_mul_f32_e32 v28, v17, v17
	v_pk_fma_f32 v[18:19], v[18:19], v[30:31], v[38:39]
	v_fmac_f32_e32 v28, v16, v16
	v_fmac_f32_e32 v28, v18, v18
	global_store_dwordx4 v[34:35], v[16:19], off
	v_fmac_f32_e32 v28, v19, v19
	s_nop 0
	v_pk_mul_f32 v[18:19], v[160:161], v[18:19]
	v_pk_mul_f32 v[16:17], v[162:163], v[16:17]
	s_nop 0
	v_cvt_pk_bf16_f32 v16, v16, v17
	v_cvt_pk_bf16_f32 v17, v18, v19
	ds_write_b64 v124, v[16:17] offset:6144
	s_nop 1
	s_waitcnt vmcnt(3)
	v_pk_fma_f32 v[12:13], v[12:13], v[24:25], v[232:233]
	s_nop 0
	v_mul_f32_e32 v16, v13, v13
	v_pk_fma_f32 v[14:15], v[14:15], v[26:27], v[234:235]
	v_fmac_f32_e32 v16, v12, v12
	v_fmac_f32_e32 v16, v14, v14
	global_store_dwordx4 v[34:35], v[12:15], off offset:64
	v_fmac_f32_e32 v16, v15, v15
	v_add_f32_e32 v16, v28, v16
	v_pk_mul_f32 v[14:15], v[156:157], v[14:15]
	v_pk_mul_f32 v[12:13], v[158:159], v[12:13]
	s_nop 0
	v_cvt_pk_bf16_f32 v12, v12, v13
	v_cvt_pk_bf16_f32 v13, v14, v15
	ds_write_b64 v120, v[12:13] offset:6144
	s_nop 1
	s_waitcnt vmcnt(3)
	v_pk_fma_f32 v[8:9], v[8:9], v[20:21], v[236:237]
	s_nop 0
	v_mul_f32_e32 v12, v9, v9
	v_pk_fma_f32 v[10:11], v[10:11], v[22:23], v[238:239]
	v_fmac_f32_e32 v12, v8, v8
	v_fmac_f32_e32 v12, v10, v10
	global_store_dwordx4 v[34:35], v[8:11], off offset:128
	v_fmac_f32_e32 v12, v11, v11
	v_add_f32_e32 v12, v16, v12
	v_pk_mul_f32 v[10:11], v[152:153], v[10:11]
	v_pk_mul_f32 v[8:9], v[154:155], v[8:9]
	s_nop 0
	v_cvt_pk_bf16_f32 v8, v8, v9
	v_cvt_pk_bf16_f32 v9, v10, v11
	ds_write_b64 v116, v[8:9] offset:6144
	s_nop 1
	s_waitcnt vmcnt(3)
	v_pk_fma_f32 v[0:1], v[0:1], v[4:5], v[240:241]
	s_nop 0
	v_mul_f32_e32 v4, v1, v1
	v_pk_fma_f32 v[2:3], v[2:3], v[6:7], v[242:243]
	v_fmac_f32_e32 v4, v0, v0
	v_fmac_f32_e32 v4, v2, v2
	global_store_dwordx4 v[34:35], v[0:3], off offset:192
	v_fmac_f32_e32 v4, v3, v3
	v_add_f32_e32 v4, v12, v4
	v_pk_mul_f32 v[2:3], v[146:147], v[2:3]
	v_pk_mul_f32 v[0:1], v[148:149], v[0:1]
	s_nop 0
	v_cvt_pk_bf16_f32 v0, v0, v1
	v_cvt_pk_bf16_f32 v1, v2, v3
	ds_write_b64 v117, v[0:1] offset:6144
	ds_bpermute_b32 v0, v170, v4
	s_waitcnt lgkmcnt(0)
	v_add_f32_e32 v0, v4, v0
	ds_bpermute_b32 v1, v171, v0
	s_and_saveexec_b64 s[6:7], vcc
	s_cbranch_execz .LBB0_124
	s_waitcnt lgkmcnt(0)
	v_add_f32_e32 v2, v0, v1
	v_lshlrev_b64 v[0:1], 6, v[32:33]
	v_lshl_add_u64 v[0:1], v[144:145], 0, v[0:1]
	global_store_dword v[0:1], v2, off sc1
	s_branch .LBB0_124

; DI unsigned pk2(float a, float b) { f32x2 v = {a, b}; bf2_t r = __builtin_convertvector(v, bf2_t); return __builtin_bit_cast(unsigned, r); }
;     static DI void run(const f32x4 (&acc)[8][4], const TileCtx& tc, const Params& p, ldsp_t wb) {
;     ...
; #pragma unroll
;         for (int n = 0; n < 4; ++n) {
;             gv[n] = *(const f32x4*)(gate + col0 + n * 16);
;             const f32x4 g1 = *(const f32x4*)(gnx + n * 16), s1 = *(const f32x4*)(scn + n * 16);
;             av[n] = g1 * (1.f + s1);
;         }
; #pragma unroll
;         for (int h = 0; h < 2; ++h) {
; #pragma unroll
;             for (int mm = 0; mm < 4; ++mm) { __builtin_amdgcn_sched_barrier(0);
;                 const int m = h * 4 + mm;
;                 const int row = tc.brow + tc.wr * 128 + m * 16 + tc.fr;
;                 float* xr = xrow_ptr(p, row) + col0;
;                 const float* xs = (EK == 1 && tc.l == 0) ? p.x + (size_t)row * DM + col0 : xr;
;                 float part = 0.f;
; #pragma unroll
;                 for (int n = 0; n < 4; ++n) {
;                     f32x4 xv = *(const f32x4*)(xs + n * 16);
;                     xv += gv[n] * acc[m][n];
;                     *(f32x4*)(xr + n * 16) = xv;
;                     if (has_next) {
;                         part += xv[0] * xv[0] + xv[1] * xv[1] + xv[2] * xv[2] + xv[3] * xv[3];
;                         const f32x4 hv = xv * av[n];
;                         u32x2 w; w[0] = pk2(hv[0], hv[1]); w[1] = pk2(hv[2], hv[3]);
;                         wave_put(wb, mm * 16 + tc.fr, n, tc.fq, w);
;                     }
;                 }
;                 if (has_next) {
;                     part += __shfl_xor(part, 16);
;                     part += __shfl_xor(part, 32);
;                     if (tc.fq == 0) ssp[(size_t)row * 16] = part;
;                 }
.LBB0_198:
	s_nop 1
	v_mov_b32_e32 v0, 0x10000
	v_lshl_add_u32 v186, v186, 13, v0
	v_pk_add_f32 v[0:1], v[174:175], 1.0 op_sel_hi:[1,0]
	v_pk_add_f32 v[2:3], v[172:173], 1.0 op_sel_hi:[1,0]
	v_pk_mul_f32 v[166:167], v[166:167], v[0:1]
	v_pk_mul_f32 v[164:165], v[164:165], v[2:3]
	v_pk_add_f32 v[0:1], v[162:163], 1.0 op_sel_hi:[1,0]
	v_pk_add_f32 v[2:3], v[160:161], 1.0 op_sel_hi:[1,0]
	v_pk_mul_f32 v[158:159], v[158:159], v[0:1]
	v_pk_mul_f32 v[156:157], v[156:157], v[2:3]
	v_pk_add_f32 v[0:1], v[154:155], 1.0 op_sel_hi:[1,0]
	v_pk_add_f32 v[2:3], v[152:153], 1.0 op_sel_hi:[1,0]
	v_and_b32_e32 v185, 63, v179
	v_pk_mul_f32 v[150:151], v[150:151], v[0:1]
	v_pk_mul_f32 v[148:149], v[148:149], v[2:3]
	v_pk_add_f32 v[0:1], v[146:147], 1.0 op_sel_hi:[1,0]
	v_pk_add_f32 v[2:3], v[144:145], 1.0 op_sel_hi:[1,0]
	v_pk_mul_f32 v[142:143], v[142:143], v[0:1]
	v_pk_mul_f32 v[144:145], v[140:141], v[2:3]
	v_lshlrev_b32_e32 v192, 2, v190
	v_lshrrev_b32_e32 v0, 5, v185
	v_and_b32_e32 v1, 7, v179
	v_lshlrev_b32_e32 v2, 3, v189
	v_lshl_add_u64 v[140:141], s[4:5], 0, v[192:193]
	s_andn2_b64 vcc, exec, s[44:45]
	v_lshl_add_u32 v146, v187, 7, v186
	v_cmp_gt_u32_e64 s[4:5], 16, v185
	v_bitop3_b32 v155, v0, v179, 7 bitop3:0x78
	v_and_b32_e32 v147, 8, v2
	v_bitop3_b32 v154, v0, v1, 2 bitop3:0x36
	v_bitop3_b32 v153, v0, v1, 4 bitop3:0x36
	v_bitop3_b32 v152, v0, v1, 6 bitop3:0x36
	v_xor_b32_e32 v230, 16, v202
	s_cbranch_vccnz .LBB0_202
	v_pk_mul_f32 v[0:1], v[166:167], v[170:171]
	v_pk_mul_f32 v[2:3], v[164:165], v[168:169]
	v_mul_f32_e32 v160, v169, v169
	v_cvt_pk_bf16_f32 v2, v2, v3
	v_cvt_pk_bf16_f32 v3, v0, v1
	v_lshlrev_b32_e32 v0, 4, v155
	v_add3_u32 v0, v146, v0, v147
	ds_write_b64 v0, v[2:3]
	s_nop 1
	v_fmac_f32_e32 v160, v168, v168
	v_fmac_f32_e32 v160, v170, v170
	v_fmac_f32_e32 v160, v171, v171
	v_cmp_lt_i32_e32 vcc, v230, v203
	s_waitcnt vmcnt(3)
	v_pk_fma_f32 v[0:1], v[136:137], v[20:21], v[232:233]
	s_nop 0
	v_mul_f32_e32 v136, v1, v1
	v_pk_fma_f32 v[2:3], v[138:139], v[22:23], v[234:235]
	v_fmac_f32_e32 v136, v0, v0
	v_fmac_f32_e32 v136, v2, v2
	global_store_dwordx4 v[182:183], v[0:3], off offset:64
	v_fmac_f32_e32 v136, v3, v3
	v_add_f32_e32 v136, v160, v136
	v_pk_mul_f32 v[2:3], v[158:159], v[2:3]
	v_pk_mul_f32 v[0:1], v[156:157], v[0:1]
	s_nop 0
	v_cvt_pk_bf16_f32 v0, v0, v1
	v_cvt_pk_bf16_f32 v1, v2, v3
	v_lshlrev_b32_e32 v2, 4, v154
	v_add3_u32 v2, v146, v2, v147
	ds_write_b64 v2, v[0:1]
	s_nop 1
	s_waitcnt vmcnt(3)
	v_pk_fma_f32 v[0:1], v[132:133], v[12:13], v[236:237]
	s_nop 0
	v_mul_f32_e32 v132, v1, v1
	v_pk_fma_f32 v[2:3], v[134:135], v[14:15], v[238:239]
	v_fmac_f32_e32 v132, v0, v0
	v_fmac_f32_e32 v132, v2, v2
	global_store_dwordx4 v[182:183], v[0:3], off offset:128
	v_fmac_f32_e32 v132, v3, v3
	v_add_f32_e32 v132, v136, v132
	v_pk_mul_f32 v[2:3], v[150:151], v[2:3]
	v_pk_mul_f32 v[0:1], v[148:149], v[0:1]
	s_nop 0
	v_cvt_pk_bf16_f32 v0, v0, v1
	v_cvt_pk_bf16_f32 v1, v2, v3
	v_lshlrev_b32_e32 v2, 4, v153
	v_add3_u32 v2, v146, v2, v147
	ds_write_b64 v2, v[0:1]
	s_nop 1
	s_waitcnt vmcnt(3)
	v_pk_fma_f32 v[0:1], v[128:129], v[4:5], v[240:241]
	s_nop 0
	v_mul_f32_e32 v128, v1, v1
	v_pk_fma_f32 v[2:3], v[130:131], v[6:7], v[242:243]
	v_fmac_f32_e32 v128, v0, v0
	v_fmac_f32_e32 v128, v2, v2
	global_store_dwordx4 v[182:183], v[0:3], off offset:192
	v_fmac_f32_e32 v128, v3, v3
	v_add_f32_e32 v128, v132, v128
	v_pk_mul_f32 v[2:3], v[142:143], v[2:3]
	v_pk_mul_f32 v[0:1], v[144:145], v[0:1]
	s_nop 0
	v_cvt_pk_bf16_f32 v0, v0, v1
	v_cvt_pk_bf16_f32 v1, v2, v3
	v_lshlrev_b32_e32 v2, 4, v152
	v_add3_u32 v2, v146, v2, v147
	ds_write_b64 v2, v[0:1]
	v_cndmask_b32_e32 v0, v202, v230, vcc
	v_lshlrev_b32_e32 v0, 2, v0
	ds_bpermute_b32 v0, v0, v128
	v_cmp_lt_i32_e32 vcc, v209, v203
	s_waitcnt lgkmcnt(0)
	v_add_f32_e32 v128, v128, v0
	v_cndmask_b32_e32 v0, v202, v209, vcc
	v_lshlrev_b32_e32 v0, 2, v0
	ds_bpermute_b32 v129, v0, v128
	s_and_saveexec_b64 s[44:45], s[4:5]
	s_cbranch_execz .LBB0_201
	v_lshlrev_b64 v[0:1], 6, v[180:181]
	s_waitcnt lgkmcnt(0)
	v_add_f32_e32 v2, v128, v129
	v_lshl_add_u64 v[0:1], v[140:141], 0, v[0:1]
	global_store_dword v[0:1], v2, off sc1

; DI unsigned pk2(float a, float b) { f32x2 v = {a, b}; bf2_t r = __builtin_convertvector(v, bf2_t); return __builtin_bit_cast(unsigned, r); }
;     static DI void run(const f32x4 (&acc)[8][4], const TileCtx& tc, const Params& p, ldsp_t wb) {
;     ...
;             for (int mm = 0; mm < 4; ++mm) { __builtin_amdgcn_sched_barrier(0);
;                 const int m = h * 4 + mm;
;                 const int row = tc.brow + tc.wr * 128 + m * 16 + tc.fr;
;                 float* xr = xrow_ptr(p, row) + col0;
;                 const float* xs = (EK == 1 && tc.l == 0) ? p.x + (size_t)row * DM + col0 : xr;
;                 float part = 0.f;
; #pragma unroll
;                 for (int n = 0; n < 4; ++n) {
;                     f32x4 xv = *(const f32x4*)(xs + n * 16);
;                     xv += gv[n] * acc[m][n];
;                     *(f32x4*)(xr + n * 16) = xv;
;                     if (has_next) {
;                         part += xv[0] * xv[0] + xv[1] * xv[1] + xv[2] * xv[2] + xv[3] * xv[3];
;                         const f32x4 hv = xv * av[n];
;                         u32x2 w; w[0] = pk2(hv[0], hv[1]); w[1] = pk2(hv[2], hv[3]);
;                         wave_put(wb, mm * 16 + tc.fr, n, tc.fq, w);
;                     }
;                 }
;                 if (has_next) {
;                     part += __shfl_xor(part, 16);
;                     part += __shfl_xor(part, 32);
;                     if (tc.fq == 0) ssp[(size_t)row * 16] = part;
;                 }
.LBB0_204:
	s_andn2_b64 vcc, exec, s[4:5]
	v_xor_b32_e32 v134, 1, v202
	v_xor_b32_e32 v135, 2, v202
	s_cbranch_vccnz .LBB0_208
	v_pk_mul_f32 v[0:1], v[166:167], v[126:127]
	v_pk_mul_f32 v[2:3], v[164:165], v[124:125]
	v_mul_f32_e32 v133, v125, v125
	v_cvt_pk_bf16_f32 v2, v2, v3
	v_cvt_pk_bf16_f32 v3, v0, v1
	v_lshlrev_b32_e32 v0, 4, v155
	v_add3_u32 v0, v146, v0, v147
	ds_write_b64 v0, v[2:3] offset:2048
	s_nop 1
	v_fmac_f32_e32 v133, v124, v124
	v_fmac_f32_e32 v133, v126, v126
	v_fmac_f32_e32 v133, v127, v127
	v_cmp_lt_i32_e32 vcc, v230, v203
	s_waitcnt vmcnt(3)
	v_pk_fma_f32 v[0:1], v[120:121], v[20:21], v[232:233]
	s_nop 0
	v_mul_f32_e32 v120, v1, v1
	v_pk_fma_f32 v[2:3], v[122:123], v[22:23], v[234:235]
	v_fmac_f32_e32 v120, v0, v0
	v_fmac_f32_e32 v120, v2, v2
	global_store_dwordx4 v[130:131], v[0:3], off offset:64
	v_fmac_f32_e32 v120, v3, v3
	v_add_f32_e32 v120, v133, v120
	v_pk_mul_f32 v[2:3], v[158:159], v[2:3]
	v_pk_mul_f32 v[0:1], v[156:157], v[0:1]
	s_nop 0
	v_cvt_pk_bf16_f32 v0, v0, v1
	v_cvt_pk_bf16_f32 v1, v2, v3
	v_lshlrev_b32_e32 v2, 4, v154
	v_add3_u32 v2, v146, v2, v147
	ds_write_b64 v2, v[0:1] offset:2048
	s_nop 1
	s_waitcnt vmcnt(3)
	v_pk_fma_f32 v[0:1], v[116:117], v[12:13], v[236:237]
	s_nop 0
	v_mul_f32_e32 v116, v1, v1
	v_pk_fma_f32 v[2:3], v[118:119], v[14:15], v[238:239]
	v_fmac_f32_e32 v116, v0, v0
	v_fmac_f32_e32 v116, v2, v2
	global_store_dwordx4 v[130:131], v[0:3], off offset:128
	v_fmac_f32_e32 v116, v3, v3
	v_add_f32_e32 v116, v120, v116
	v_pk_mul_f32 v[2:3], v[150:151], v[2:3]
	v_pk_mul_f32 v[0:1], v[148:149], v[0:1]
	s_nop 0
	v_cvt_pk_bf16_f32 v0, v0, v1
	v_cvt_pk_bf16_f32 v1, v2, v3
	v_lshlrev_b32_e32 v2, 4, v153
	v_add3_u32 v2, v146, v2, v147
	ds_write_b64 v2, v[0:1] offset:2048
	s_nop 1
	s_waitcnt vmcnt(3)
	v_pk_fma_f32 v[0:1], v[112:113], v[4:5], v[240:241]
	s_nop 0
	v_mul_f32_e32 v112, v1, v1
	v_pk_fma_f32 v[2:3], v[114:115], v[6:7], v[242:243]
	v_fmac_f32_e32 v112, v0, v0
	v_fmac_f32_e32 v112, v2, v2
	global_store_dwordx4 v[130:131], v[0:3], off offset:192
	v_fmac_f32_e32 v112, v3, v3
	v_add_f32_e32 v112, v116, v112
	v_pk_mul_f32 v[2:3], v[142:143], v[2:3]
	v_pk_mul_f32 v[0:1], v[144:145], v[0:1]
	s_nop 0
	v_cvt_pk_bf16_f32 v0, v0, v1
	v_cvt_pk_bf16_f32 v1, v2, v3
	v_lshlrev_b32_e32 v2, 4, v152
	v_add3_u32 v2, v146, v2, v147
	ds_write_b64 v2, v[0:1] offset:2048
	v_cndmask_b32_e32 v0, v202, v230, vcc
	v_lshlrev_b32_e32 v0, 2, v0
	ds_bpermute_b32 v0, v0, v112
	v_cmp_lt_i32_e32 vcc, v209, v203
	s_waitcnt lgkmcnt(0)
	v_add_f32_e32 v112, v112, v0
	v_cndmask_b32_e32 v0, v202, v209, vcc
	v_lshlrev_b32_e32 v0, 2, v0
	ds_bpermute_b32 v113, v0, v112
	v_cmp_gt_u32_e32 vcc, 16, v185
	s_and_saveexec_b64 s[4:5], vcc
	s_cbranch_execz .LBB0_207
	v_lshlrev_b64 v[0:1], 6, v[128:129]
	s_waitcnt lgkmcnt(0)
	v_add_f32_e32 v2, v112, v113
	v_lshl_add_u64 v[0:1], v[140:141], 0, v[0:1]
	global_store_dword v[0:1], v2, off sc1

; DI unsigned pk2(float a, float b) { f32x2 v = {a, b}; bf2_t r = __builtin_convertvector(v, bf2_t); return __builtin_bit_cast(unsigned, r); }
;     static DI void run(const f32x4 (&acc)[8][4], const TileCtx& tc, const Params& p, ldsp_t wb) {
;     ...
;             for (int mm = 0; mm < 4; ++mm) { __builtin_amdgcn_sched_barrier(0);
;                 const int m = h * 4 + mm;
;                 const int row = tc.brow + tc.wr * 128 + m * 16 + tc.fr;
;                 float* xr = xrow_ptr(p, row) + col0;
;                 const float* xs = (EK == 1 && tc.l == 0) ? p.x + (size_t)row * DM + col0 : xr;
;                 float part = 0.f;
; #pragma unroll
;                 for (int n = 0; n < 4; ++n) {
;                     f32x4 xv = *(const f32x4*)(xs + n * 16);
;                     xv += gv[n] * acc[m][n];
;                     *(f32x4*)(xr + n * 16) = xv;
;                     if (has_next) {
;                         part += xv[0] * xv[0] + xv[1] * xv[1] + xv[2] * xv[2] + xv[3] * xv[3];
;                         const f32x4 hv = xv * av[n];
;                         u32x2 w; w[0] = pk2(hv[0], hv[1]); w[1] = pk2(hv[2], hv[3]);
;                         wave_put(wb, mm * 16 + tc.fr, n, tc.fq, w);
;                     }
;                 }
;                 if (has_next) {
;                     part += __shfl_xor(part, 16);
;                     part += __shfl_xor(part, 32);
;                     if (tc.fq == 0) ssp[(size_t)row * 16] = part;
;                 }
.LBB0_210:
	s_andn2_b64 vcc, exec, s[4:5]
	s_cbranch_vccnz .LBB0_214
	v_pk_mul_f32 v[0:1], v[166:167], v[110:111]
	v_pk_mul_f32 v[2:3], v[164:165], v[108:109]
	v_mul_f32_e32 v116, v109, v109
	v_cvt_pk_bf16_f32 v2, v2, v3
	v_cvt_pk_bf16_f32 v3, v0, v1
	v_lshlrev_b32_e32 v0, 4, v155
	v_add3_u32 v0, v146, v0, v147
	ds_write_b64 v0, v[2:3] offset:4096
	s_nop 1
	v_fmac_f32_e32 v116, v108, v108
	v_fmac_f32_e32 v116, v110, v110
	v_fmac_f32_e32 v116, v111, v111
	v_cmp_lt_i32_e32 vcc, v230, v203
	s_waitcnt vmcnt(3)
	v_pk_fma_f32 v[0:1], v[104:105], v[20:21], v[232:233]
	s_nop 0
	v_mul_f32_e32 v104, v1, v1
	v_pk_fma_f32 v[2:3], v[106:107], v[22:23], v[234:235]
	v_fmac_f32_e32 v104, v0, v0
	v_fmac_f32_e32 v104, v2, v2
	global_store_dwordx4 v[114:115], v[0:3], off offset:64
	v_fmac_f32_e32 v104, v3, v3
	v_add_f32_e32 v104, v116, v104
	v_pk_mul_f32 v[2:3], v[158:159], v[2:3]
	v_pk_mul_f32 v[0:1], v[156:157], v[0:1]
	s_nop 0
	v_cvt_pk_bf16_f32 v0, v0, v1
	v_cvt_pk_bf16_f32 v1, v2, v3
	v_lshlrev_b32_e32 v2, 4, v154
	v_add3_u32 v2, v146, v2, v147
	ds_write_b64 v2, v[0:1] offset:4096
	s_nop 1
	s_waitcnt vmcnt(3)
	v_pk_fma_f32 v[0:1], v[100:101], v[12:13], v[236:237]
	s_nop 0
	v_mul_f32_e32 v100, v1, v1
	v_pk_fma_f32 v[2:3], v[102:103], v[14:15], v[238:239]
	v_fmac_f32_e32 v100, v0, v0
	v_fmac_f32_e32 v100, v2, v2
	global_store_dwordx4 v[114:115], v[0:3], off offset:128
	v_fmac_f32_e32 v100, v3, v3
	v_add_f32_e32 v100, v104, v100
	v_pk_mul_f32 v[2:3], v[150:151], v[2:3]
	v_pk_mul_f32 v[0:1], v[148:149], v[0:1]
	s_nop 0
	v_cvt_pk_bf16_f32 v0, v0, v1
	v_cvt_pk_bf16_f32 v1, v2, v3
	v_lshlrev_b32_e32 v2, 4, v153
	v_add3_u32 v2, v146, v2, v147
	ds_write_b64 v2, v[0:1] offset:4096
	s_nop 1
	s_waitcnt vmcnt(3)
	v_pk_fma_f32 v[0:1], v[96:97], v[4:5], v[240:241]
	s_nop 0
	v_mul_f32_e32 v96, v1, v1
	v_pk_fma_f32 v[2:3], v[98:99], v[6:7], v[242:243]
	v_fmac_f32_e32 v96, v0, v0
	v_fmac_f32_e32 v96, v2, v2
	global_store_dwordx4 v[114:115], v[0:3], off offset:192
	v_fmac_f32_e32 v96, v3, v3
	v_add_f32_e32 v96, v100, v96
	v_pk_mul_f32 v[2:3], v[142:143], v[2:3]
	v_pk_mul_f32 v[0:1], v[144:145], v[0:1]
	s_nop 0
	v_cvt_pk_bf16_f32 v0, v0, v1
	v_cvt_pk_bf16_f32 v1, v2, v3
	v_lshlrev_b32_e32 v2, 4, v152
	v_add3_u32 v2, v146, v2, v147
	ds_write_b64 v2, v[0:1] offset:4096
	v_cndmask_b32_e32 v0, v202, v230, vcc
	v_lshlrev_b32_e32 v0, 2, v0
	ds_bpermute_b32 v0, v0, v96
	v_cmp_lt_i32_e32 vcc, v209, v203
	s_waitcnt lgkmcnt(0)
	v_add_f32_e32 v96, v96, v0
	v_cndmask_b32_e32 v0, v202, v209, vcc
	v_lshlrev_b32_e32 v0, 2, v0
	ds_bpermute_b32 v97, v0, v96
	v_cmp_gt_u32_e32 vcc, 16, v185
	s_and_saveexec_b64 s[4:5], vcc
	s_cbranch_execz .LBB0_213
	v_lshlrev_b64 v[0:1], 6, v[112:113]
	s_waitcnt lgkmcnt(0)
	v_add_f32_e32 v2, v96, v97
	v_lshl_add_u64 v[0:1], v[140:141], 0, v[0:1]
	global_store_dword v[0:1], v2, off sc1

; DI unsigned pk2(float a, float b) { f32x2 v = {a, b}; bf2_t r = __builtin_convertvector(v, bf2_t); return __builtin_bit_cast(unsigned, r); }
;     static DI void run(const f32x4 (&acc)[8][4], const TileCtx& tc, const Params& p, ldsp_t wb) {
;     ...
;             for (int mm = 0; mm < 4; ++mm) { __builtin_amdgcn_sched_barrier(0);
;                 const int m = h * 4 + mm;
;                 const int row = tc.brow + tc.wr * 128 + m * 16 + tc.fr;
;                 float* xr = xrow_ptr(p, row) + col0;
;                 const float* xs = (EK == 1 && tc.l == 0) ? p.x + (size_t)row * DM + col0 : xr;
;                 float part = 0.f;
; #pragma unroll
;                 for (int n = 0; n < 4; ++n) {
;                     f32x4 xv = *(const f32x4*)(xs + n * 16);
;                     xv += gv[n] * acc[m][n];
;                     *(f32x4*)(xr + n * 16) = xv;
;                     if (has_next) {
;                         part += xv[0] * xv[0] + xv[1] * xv[1] + xv[2] * xv[2] + xv[3] * xv[3];
;                         const f32x4 hv = xv * av[n];
;                         u32x2 w; w[0] = pk2(hv[0], hv[1]); w[1] = pk2(hv[2], hv[3]);
;                         wave_put(wb, mm * 16 + tc.fr, n, tc.fq, w);
;                     }
;                 }
;                 if (has_next) {
;                     part += __shfl_xor(part, 16);
;                     part += __shfl_xor(part, 32);
;                     if (tc.fq == 0) ssp[(size_t)row * 16] = part;
;                 }
.LBB0_216:
	s_andn2_b64 vcc, exec, s[4:5]
	s_cbranch_vccnz .LBB0_220
	v_pk_mul_f32 v[0:1], v[166:167], v[94:95]
	v_pk_mul_f32 v[2:3], v[164:165], v[92:93]
	v_mul_f32_e32 v100, v93, v93
	v_cvt_pk_bf16_f32 v2, v2, v3
	v_cvt_pk_bf16_f32 v3, v0, v1
	v_lshlrev_b32_e32 v0, 4, v155
	v_add3_u32 v0, v146, v0, v147
	ds_write_b64 v0, v[2:3] offset:6144
	s_nop 1
	v_fmac_f32_e32 v100, v92, v92
	v_fmac_f32_e32 v100, v94, v94
	v_fmac_f32_e32 v100, v95, v95
	v_cmp_lt_i32_e32 vcc, v230, v203
	s_waitcnt vmcnt(3)
	v_pk_fma_f32 v[0:1], v[88:89], v[20:21], v[232:233]
	s_nop 0
	v_mul_f32_e32 v88, v1, v1
	v_pk_fma_f32 v[2:3], v[90:91], v[22:23], v[234:235]
	v_fmac_f32_e32 v88, v0, v0
	v_fmac_f32_e32 v88, v2, v2
	global_store_dwordx4 v[98:99], v[0:3], off offset:64
	v_fmac_f32_e32 v88, v3, v3
	v_add_f32_e32 v88, v100, v88
	v_pk_mul_f32 v[2:3], v[158:159], v[2:3]
	v_pk_mul_f32 v[0:1], v[156:157], v[0:1]
	s_nop 0
	v_cvt_pk_bf16_f32 v0, v0, v1
	v_cvt_pk_bf16_f32 v1, v2, v3
	v_lshlrev_b32_e32 v2, 4, v154
	v_add3_u32 v2, v146, v2, v147
	ds_write_b64 v2, v[0:1] offset:6144
	s_nop 1
	s_waitcnt vmcnt(3)
	v_pk_fma_f32 v[0:1], v[84:85], v[12:13], v[236:237]
	s_nop 0
	v_mul_f32_e32 v84, v1, v1
	v_pk_fma_f32 v[2:3], v[86:87], v[14:15], v[238:239]
	v_fmac_f32_e32 v84, v0, v0
	v_fmac_f32_e32 v84, v2, v2
	global_store_dwordx4 v[98:99], v[0:3], off offset:128
	v_fmac_f32_e32 v84, v3, v3
	v_add_f32_e32 v84, v88, v84
	v_pk_mul_f32 v[2:3], v[150:151], v[2:3]
	v_pk_mul_f32 v[0:1], v[148:149], v[0:1]
	s_nop 0
	v_cvt_pk_bf16_f32 v0, v0, v1
	v_cvt_pk_bf16_f32 v1, v2, v3
	v_lshlrev_b32_e32 v2, 4, v153
	v_add3_u32 v2, v146, v2, v147
	ds_write_b64 v2, v[0:1] offset:6144
	s_nop 1
	s_waitcnt vmcnt(3)
	v_pk_fma_f32 v[0:1], v[80:81], v[4:5], v[240:241]
	s_nop 0
	v_mul_f32_e32 v80, v1, v1
	v_pk_fma_f32 v[2:3], v[82:83], v[6:7], v[242:243]
	v_fmac_f32_e32 v80, v0, v0
	v_fmac_f32_e32 v80, v2, v2
	global_store_dwordx4 v[98:99], v[0:3], off offset:192
	v_fmac_f32_e32 v80, v3, v3
	v_add_f32_e32 v80, v84, v80
	v_pk_mul_f32 v[2:3], v[142:143], v[2:3]
	v_pk_mul_f32 v[0:1], v[144:145], v[0:1]
	s_nop 0
	v_cvt_pk_bf16_f32 v0, v0, v1
	v_cvt_pk_bf16_f32 v1, v2, v3
	v_lshlrev_b32_e32 v2, 4, v152
	v_add3_u32 v2, v146, v2, v147
	ds_write_b64 v2, v[0:1] offset:6144
	v_cndmask_b32_e32 v0, v202, v230, vcc
	v_lshlrev_b32_e32 v0, 2, v0
	ds_bpermute_b32 v0, v0, v80
	v_cmp_lt_i32_e32 vcc, v209, v203
	s_waitcnt lgkmcnt(0)
	v_add_f32_e32 v80, v80, v0
	v_cndmask_b32_e32 v0, v202, v209, vcc
	v_lshlrev_b32_e32 v0, 2, v0
	ds_bpermute_b32 v81, v0, v80
	v_cmp_gt_u32_e32 vcc, 16, v185
	s_and_saveexec_b64 s[4:5], vcc
	s_cbranch_execz .LBB0_219
	v_lshlrev_b64 v[0:1], 6, v[96:97]
	s_waitcnt lgkmcnt(0)
	v_add_f32_e32 v2, v80, v81
	v_lshl_add_u64 v[0:1], v[140:141], 0, v[0:1]
	global_store_dword v[0:1], v2, off sc1

; DI unsigned pk2(float a, float b) { f32x2 v = {a, b}; bf2_t r = __builtin_convertvector(v, bf2_t); return __builtin_bit_cast(unsigned, r); }
;     static DI void run(const f32x4 (&acc)[8][4], const TileCtx& tc, const Params& p, ldsp_t wb) {
;     ...
;             for (int mm = 0; mm < 4; ++mm) { __builtin_amdgcn_sched_barrier(0);
;                 const int m = h * 4 + mm;
;                 const int row = tc.brow + tc.wr * 128 + m * 16 + tc.fr;
;                 float* xr = xrow_ptr(p, row) + col0;
;                 const float* xs = (EK == 1 && tc.l == 0) ? p.x + (size_t)row * DM + col0 : xr;
;                 float part = 0.f;
; #pragma unroll
;                 for (int n = 0; n < 4; ++n) {
;                     f32x4 xv = *(const f32x4*)(xs + n * 16);
;                     xv += gv[n] * acc[m][n];
;                     *(f32x4*)(xr + n * 16) = xv;
;                     if (has_next) {
;                         part += xv[0] * xv[0] + xv[1] * xv[1] + xv[2] * xv[2] + xv[3] * xv[3];
;                         const f32x4 hv = xv * av[n];
;                         u32x2 w; w[0] = pk2(hv[0], hv[1]); w[1] = pk2(hv[2], hv[3]);
;                         wave_put(wb, mm * 16 + tc.fr, n, tc.fq, w);
;                     }
;                 }
;                 if (has_next) {
;                     part += __shfl_xor(part, 16);
;                     part += __shfl_xor(part, 32);
;                     if (tc.fq == 0) ssp[(size_t)row * 16] = part;
;                 }
.LBB0_222:
	s_andn2_b64 vcc, exec, s[4:5]
	s_cbranch_vccnz .LBB0_226
	v_pk_mul_f32 v[0:1], v[166:167], v[78:79]
	v_pk_mul_f32 v[2:3], v[164:165], v[76:77]
	v_mul_f32_e32 v81, v77, v77
	v_cvt_pk_bf16_f32 v2, v2, v3
	v_cvt_pk_bf16_f32 v3, v0, v1
	v_lshlrev_b32_e32 v0, 4, v155
	v_add3_u32 v0, v146, v0, v147
	ds_write_b64 v0, v[2:3]
	s_nop 1
	v_fmac_f32_e32 v81, v76, v76
	v_fmac_f32_e32 v81, v78, v78
	v_fmac_f32_e32 v81, v79, v79
	v_cmp_lt_i32_e32 vcc, v230, v203
	s_waitcnt vmcnt(3)
	v_pk_fma_f32 v[0:1], v[72:73], v[20:21], v[232:233]
	s_nop 0
	v_mul_f32_e32 v72, v1, v1
	v_pk_fma_f32 v[2:3], v[74:75], v[22:23], v[234:235]
	v_fmac_f32_e32 v72, v0, v0
	v_fmac_f32_e32 v72, v2, v2
	global_store_dwordx4 v[84:85], v[0:3], off offset:64
	v_fmac_f32_e32 v72, v3, v3
	v_add_f32_e32 v72, v81, v72
	v_pk_mul_f32 v[2:3], v[158:159], v[2:3]
	v_pk_mul_f32 v[0:1], v[156:157], v[0:1]
	s_nop 0
	v_cvt_pk_bf16_f32 v0, v0, v1
	v_cvt_pk_bf16_f32 v1, v2, v3
	v_lshlrev_b32_e32 v2, 4, v154
	v_add3_u32 v2, v146, v2, v147
	ds_write_b64 v2, v[0:1]
	s_nop 1
	s_waitcnt vmcnt(3)
	v_pk_fma_f32 v[0:1], v[194:195], v[12:13], v[236:237]
	s_nop 0
	v_mul_f32_e32 v73, v1, v1
	v_pk_fma_f32 v[2:3], v[196:197], v[14:15], v[238:239]
	v_fmac_f32_e32 v73, v0, v0
	v_fmac_f32_e32 v73, v2, v2
	global_store_dwordx4 v[84:85], v[0:3], off offset:128
	v_fmac_f32_e32 v73, v3, v3
	v_add_f32_e32 v72, v72, v73
	v_pk_mul_f32 v[2:3], v[150:151], v[2:3]
	v_pk_mul_f32 v[0:1], v[148:149], v[0:1]
	s_nop 0
	v_cvt_pk_bf16_f32 v0, v0, v1
	v_cvt_pk_bf16_f32 v1, v2, v3
	v_lshlrev_b32_e32 v2, 4, v153
	v_add3_u32 v2, v146, v2, v147
	ds_write_b64 v2, v[0:1]
	s_nop 1
	s_waitcnt vmcnt(3)
	v_pk_fma_f32 v[0:1], v[64:65], v[4:5], v[240:241]
	s_nop 0
	v_mul_f32_e32 v64, v1, v1
	v_pk_fma_f32 v[2:3], v[66:67], v[6:7], v[242:243]
	v_fmac_f32_e32 v64, v0, v0
	v_fmac_f32_e32 v64, v2, v2
	global_store_dwordx4 v[84:85], v[0:3], off offset:192
	v_fmac_f32_e32 v64, v3, v3
	v_add_f32_e32 v64, v72, v64
	v_pk_mul_f32 v[2:3], v[142:143], v[2:3]
	v_pk_mul_f32 v[0:1], v[144:145], v[0:1]
	s_nop 0
	v_cvt_pk_bf16_f32 v0, v0, v1
	v_cvt_pk_bf16_f32 v1, v2, v3
	v_lshlrev_b32_e32 v2, 4, v152
	v_add3_u32 v2, v146, v2, v147
	ds_write_b64 v2, v[0:1]
	v_cndmask_b32_e32 v0, v202, v230, vcc
	v_lshlrev_b32_e32 v0, 2, v0
	ds_bpermute_b32 v0, v0, v64
	v_cmp_lt_i32_e32 vcc, v209, v203
	s_waitcnt lgkmcnt(0)
	v_add_f32_e32 v64, v64, v0
	v_cndmask_b32_e32 v0, v202, v209, vcc
	v_lshlrev_b32_e32 v0, 2, v0
	ds_bpermute_b32 v65, v0, v64
	v_cmp_gt_u32_e32 vcc, 16, v185
	s_and_saveexec_b64 s[4:5], vcc
	s_cbranch_execz .LBB0_225
	v_lshlrev_b64 v[0:1], 6, v[82:83]
	s_waitcnt lgkmcnt(0)
	v_add_f32_e32 v2, v64, v65
	v_lshl_add_u64 v[0:1], v[140:141], 0, v[0:1]
	global_store_dword v[0:1], v2, off sc1

; DI unsigned pk2(float a, float b) { f32x2 v = {a, b}; bf2_t r = __builtin_convertvector(v, bf2_t); return __builtin_bit_cast(unsigned, r); }
;     static DI void run(const f32x4 (&acc)[8][4], const TileCtx& tc, const Params& p, ldsp_t wb) {
;     ...
;             for (int mm = 0; mm < 4; ++mm) { __builtin_amdgcn_sched_barrier(0);
;                 const int m = h * 4 + mm;
;                 const int row = tc.brow + tc.wr * 128 + m * 16 + tc.fr;
;                 float* xr = xrow_ptr(p, row) + col0;
;                 const float* xs = (EK == 1 && tc.l == 0) ? p.x + (size_t)row * DM + col0 : xr;
;                 float part = 0.f;
; #pragma unroll
;                 for (int n = 0; n < 4; ++n) {
;                     f32x4 xv = *(const f32x4*)(xs + n * 16);
;                     xv += gv[n] * acc[m][n];
;                     *(f32x4*)(xr + n * 16) = xv;
;                     if (has_next) {
;                         part += xv[0] * xv[0] + xv[1] * xv[1] + xv[2] * xv[2] + xv[3] * xv[3];
;                         const f32x4 hv = xv * av[n];
;                         u32x2 w; w[0] = pk2(hv[0], hv[1]); w[1] = pk2(hv[2], hv[3]);
;                         wave_put(wb, mm * 16 + tc.fr, n, tc.fq, w);
;                     }
;                 }
;                 if (has_next) {
;                     part += __shfl_xor(part, 16);
;                     part += __shfl_xor(part, 32);
;                     if (tc.fq == 0) ssp[(size_t)row * 16] = part;
;                 }
.LBB0_228:
	s_andn2_b64 vcc, exec, s[4:5]
	s_cbranch_vccnz .LBB0_232
	v_pk_mul_f32 v[0:1], v[166:167], v[62:63]
	v_pk_mul_f32 v[2:3], v[164:165], v[60:61]
	v_mul_f32_e32 v72, v61, v61
	v_cvt_pk_bf16_f32 v2, v2, v3
	v_cvt_pk_bf16_f32 v3, v0, v1
	v_lshlrev_b32_e32 v0, 4, v155
	v_add3_u32 v0, v146, v0, v147
	ds_write_b64 v0, v[2:3] offset:2048
	s_nop 1
	v_fmac_f32_e32 v72, v60, v60
	v_fmac_f32_e32 v72, v62, v62
	v_fmac_f32_e32 v72, v63, v63
	v_cmp_lt_i32_e32 vcc, v230, v203
	s_waitcnt vmcnt(3)
	v_pk_fma_f32 v[0:1], v[56:57], v[20:21], v[232:233]
	s_nop 0
	v_mul_f32_e32 v56, v1, v1
	v_pk_fma_f32 v[2:3], v[58:59], v[22:23], v[234:235]
	v_fmac_f32_e32 v56, v0, v0
	v_fmac_f32_e32 v56, v2, v2
	global_store_dwordx4 v[66:67], v[0:3], off offset:64
	v_fmac_f32_e32 v56, v3, v3
	v_add_f32_e32 v56, v72, v56
	v_pk_mul_f32 v[2:3], v[158:159], v[2:3]
	v_pk_mul_f32 v[0:1], v[156:157], v[0:1]
	s_nop 0
	v_cvt_pk_bf16_f32 v0, v0, v1
	v_cvt_pk_bf16_f32 v1, v2, v3
	v_lshlrev_b32_e32 v2, 4, v154
	v_add3_u32 v2, v146, v2, v147
	ds_write_b64 v2, v[0:1] offset:2048
	s_nop 1
	s_waitcnt vmcnt(3)
	v_pk_fma_f32 v[0:1], v[52:53], v[12:13], v[236:237]
	s_nop 0
	v_mul_f32_e32 v52, v1, v1
	v_pk_fma_f32 v[2:3], v[54:55], v[14:15], v[238:239]
	v_fmac_f32_e32 v52, v0, v0
	v_fmac_f32_e32 v52, v2, v2
	global_store_dwordx4 v[66:67], v[0:3], off offset:128
	v_fmac_f32_e32 v52, v3, v3
	v_add_f32_e32 v52, v56, v52
	v_pk_mul_f32 v[2:3], v[150:151], v[2:3]
	v_pk_mul_f32 v[0:1], v[148:149], v[0:1]
	s_nop 0
	v_cvt_pk_bf16_f32 v0, v0, v1
	v_cvt_pk_bf16_f32 v1, v2, v3
	v_lshlrev_b32_e32 v2, 4, v153
	v_add3_u32 v2, v146, v2, v147
	ds_write_b64 v2, v[0:1] offset:2048
	s_nop 1
	s_waitcnt vmcnt(3)
	v_pk_fma_f32 v[0:1], v[48:49], v[4:5], v[240:241]
	s_nop 0
	v_mul_f32_e32 v48, v1, v1
	v_pk_fma_f32 v[2:3], v[50:51], v[6:7], v[242:243]
	v_fmac_f32_e32 v48, v0, v0
	v_fmac_f32_e32 v48, v2, v2
	global_store_dwordx4 v[66:67], v[0:3], off offset:192
	v_fmac_f32_e32 v48, v3, v3
	v_add_f32_e32 v48, v52, v48
	v_pk_mul_f32 v[2:3], v[142:143], v[2:3]
	v_pk_mul_f32 v[0:1], v[144:145], v[0:1]
	s_nop 0
	v_cvt_pk_bf16_f32 v0, v0, v1
	v_cvt_pk_bf16_f32 v1, v2, v3
	v_lshlrev_b32_e32 v2, 4, v152
	v_add3_u32 v2, v146, v2, v147
	ds_write_b64 v2, v[0:1] offset:2048
	v_cndmask_b32_e32 v0, v202, v230, vcc
	v_lshlrev_b32_e32 v0, 2, v0
	ds_bpermute_b32 v0, v0, v48
	v_cmp_lt_i32_e32 vcc, v209, v203
	s_waitcnt lgkmcnt(0)
	v_add_f32_e32 v48, v48, v0
	v_cndmask_b32_e32 v0, v202, v209, vcc
	v_lshlrev_b32_e32 v0, 2, v0
	ds_bpermute_b32 v49, v0, v48
	v_cmp_gt_u32_e32 vcc, 16, v185
	s_and_saveexec_b64 s[4:5], vcc
	s_cbranch_execz .LBB0_231
	v_lshlrev_b64 v[0:1], 6, v[64:65]
	s_waitcnt lgkmcnt(0)
	v_add_f32_e32 v2, v48, v49
	v_lshl_add_u64 v[0:1], v[140:141], 0, v[0:1]
	global_store_dword v[0:1], v2, off sc1

; DI unsigned pk2(float a, float b) { f32x2 v = {a, b}; bf2_t r = __builtin_convertvector(v, bf2_t); return __builtin_bit_cast(unsigned, r); }
;     static DI void run(const f32x4 (&acc)[8][4], const TileCtx& tc, const Params& p, ldsp_t wb) {
;     ...
;             for (int mm = 0; mm < 4; ++mm) { __builtin_amdgcn_sched_barrier(0);
;                 const int m = h * 4 + mm;
;                 const int row = tc.brow + tc.wr * 128 + m * 16 + tc.fr;
;                 float* xr = xrow_ptr(p, row) + col0;
;                 const float* xs = (EK == 1 && tc.l == 0) ? p.x + (size_t)row * DM + col0 : xr;
;                 float part = 0.f;
; #pragma unroll
;                 for (int n = 0; n < 4; ++n) {
;                     f32x4 xv = *(const f32x4*)(xs + n * 16);
;                     xv += gv[n] * acc[m][n];
;                     *(f32x4*)(xr + n * 16) = xv;
;                     if (has_next) {
;                         part += xv[0] * xv[0] + xv[1] * xv[1] + xv[2] * xv[2] + xv[3] * xv[3];
;                         const f32x4 hv = xv * av[n];
;                         u32x2 w; w[0] = pk2(hv[0], hv[1]); w[1] = pk2(hv[2], hv[3]);
;                         wave_put(wb, mm * 16 + tc.fr, n, tc.fq, w);
;                     }
;                 }
;                 if (has_next) {
;                     part += __shfl_xor(part, 16);
;                     part += __shfl_xor(part, 32);
;                     if (tc.fq == 0) ssp[(size_t)row * 16] = part;
;                 }
.LBB0_234:
	s_andn2_b64 vcc, exec, s[4:5]
	s_cbranch_vccnz .LBB0_238
	v_pk_mul_f32 v[0:1], v[166:167], v[46:47]
	v_pk_mul_f32 v[2:3], v[164:165], v[44:45]
	v_mul_f32_e32 v52, v45, v45
	v_cvt_pk_bf16_f32 v2, v2, v3
	v_cvt_pk_bf16_f32 v3, v0, v1
	v_lshlrev_b32_e32 v0, 4, v155
	v_add3_u32 v0, v146, v0, v147
	ds_write_b64 v0, v[2:3] offset:4096
	s_nop 1
	v_fmac_f32_e32 v52, v44, v44
	v_fmac_f32_e32 v52, v46, v46
	v_fmac_f32_e32 v52, v47, v47
	v_cmp_lt_i32_e32 vcc, v230, v203
	s_waitcnt vmcnt(3)
	v_pk_fma_f32 v[0:1], v[40:41], v[20:21], v[232:233]
	s_nop 0
	v_mul_f32_e32 v40, v1, v1
	v_pk_fma_f32 v[2:3], v[42:43], v[22:23], v[234:235]
	v_fmac_f32_e32 v40, v0, v0
	v_fmac_f32_e32 v40, v2, v2
	global_store_dwordx4 v[50:51], v[0:3], off offset:64
	v_fmac_f32_e32 v40, v3, v3
	v_add_f32_e32 v40, v52, v40
	v_pk_mul_f32 v[2:3], v[158:159], v[2:3]
	v_pk_mul_f32 v[0:1], v[156:157], v[0:1]
	s_nop 0
	v_cvt_pk_bf16_f32 v0, v0, v1
	v_cvt_pk_bf16_f32 v1, v2, v3
	v_lshlrev_b32_e32 v2, 4, v154
	v_add3_u32 v2, v146, v2, v147
	ds_write_b64 v2, v[0:1] offset:4096
	s_nop 1
	s_waitcnt vmcnt(3)
	v_pk_fma_f32 v[0:1], v[36:37], v[12:13], v[236:237]
	s_nop 0
	v_mul_f32_e32 v36, v1, v1
	v_pk_fma_f32 v[2:3], v[38:39], v[14:15], v[238:239]
	v_fmac_f32_e32 v36, v0, v0
	v_fmac_f32_e32 v36, v2, v2
	global_store_dwordx4 v[50:51], v[0:3], off offset:128
	v_fmac_f32_e32 v36, v3, v3
	v_add_f32_e32 v36, v40, v36
	v_pk_mul_f32 v[2:3], v[150:151], v[2:3]
	v_pk_mul_f32 v[0:1], v[148:149], v[0:1]
	s_nop 0
	v_cvt_pk_bf16_f32 v0, v0, v1
	v_cvt_pk_bf16_f32 v1, v2, v3
	v_lshlrev_b32_e32 v2, 4, v153
	v_add3_u32 v2, v146, v2, v147
	ds_write_b64 v2, v[0:1] offset:4096
	s_nop 1
	s_waitcnt vmcnt(3)
	v_pk_fma_f32 v[0:1], v[32:33], v[4:5], v[240:241]
	s_nop 0
	v_mul_f32_e32 v32, v1, v1
	v_pk_fma_f32 v[2:3], v[34:35], v[6:7], v[242:243]
	v_fmac_f32_e32 v32, v0, v0
	v_fmac_f32_e32 v32, v2, v2
	global_store_dwordx4 v[50:51], v[0:3], off offset:192
	v_fmac_f32_e32 v32, v3, v3
	v_add_f32_e32 v32, v36, v32
	v_pk_mul_f32 v[2:3], v[142:143], v[2:3]
	v_pk_mul_f32 v[0:1], v[144:145], v[0:1]
	s_nop 0
	v_cvt_pk_bf16_f32 v0, v0, v1
	v_cvt_pk_bf16_f32 v1, v2, v3
	v_lshlrev_b32_e32 v2, 4, v152
	v_add3_u32 v2, v146, v2, v147
	ds_write_b64 v2, v[0:1] offset:4096
	v_cndmask_b32_e32 v0, v202, v230, vcc
	v_lshlrev_b32_e32 v0, 2, v0
	ds_bpermute_b32 v0, v0, v32
	v_cmp_lt_i32_e32 vcc, v209, v203
	s_waitcnt lgkmcnt(0)
	v_add_f32_e32 v32, v32, v0
	v_cndmask_b32_e32 v0, v202, v209, vcc
	v_lshlrev_b32_e32 v0, 2, v0
	ds_bpermute_b32 v33, v0, v32
	v_cmp_gt_u32_e32 vcc, 16, v185
	s_and_saveexec_b64 s[4:5], vcc
	s_cbranch_execz .LBB0_237
	v_lshlrev_b64 v[0:1], 6, v[48:49]
	s_waitcnt lgkmcnt(0)
	v_add_f32_e32 v2, v32, v33
	v_lshl_add_u64 v[0:1], v[140:141], 0, v[0:1]
	global_store_dword v[0:1], v2, off sc1

; DI unsigned pk2(float a, float b) { f32x2 v = {a, b}; bf2_t r = __builtin_convertvector(v, bf2_t); return __builtin_bit_cast(unsigned, r); }
;     static DI void run(const f32x4 (&acc)[8][4], const TileCtx& tc, const Params& p, ldsp_t wb) {
;     ...
;             for (int mm = 0; mm < 4; ++mm) { __builtin_amdgcn_sched_barrier(0);
;                 const int m = h * 4 + mm;
;                 const int row = tc.brow + tc.wr * 128 + m * 16 + tc.fr;
;                 float* xr = xrow_ptr(p, row) + col0;
;                 const float* xs = (EK == 1 && tc.l == 0) ? p.x + (size_t)row * DM + col0 : xr;
;                 float part = 0.f;
; #pragma unroll
;                 for (int n = 0; n < 4; ++n) {
;                     f32x4 xv = *(const f32x4*)(xs + n * 16);
;                     xv += gv[n] * acc[m][n];
;                     *(f32x4*)(xr + n * 16) = xv;
;                     if (has_next) {
;                         part += xv[0] * xv[0] + xv[1] * xv[1] + xv[2] * xv[2] + xv[3] * xv[3];
;                         const f32x4 hv = xv * av[n];
;                         u32x2 w; w[0] = pk2(hv[0], hv[1]); w[1] = pk2(hv[2], hv[3]);
;                         wave_put(wb, mm * 16 + tc.fr, n, tc.fq, w);
;                     }
;                 }
;                 if (has_next) {
;                     part += __shfl_xor(part, 16);
;                     part += __shfl_xor(part, 32);
;                     if (tc.fq == 0) ssp[(size_t)row * 16] = part;
;                 }
.LBB0_240:
	s_andn2_b64 vcc, exec, s[4:5]
	s_cbranch_vccnz .LBB0_183
	v_pk_mul_f32 v[0:1], v[166:167], v[26:27]
	v_pk_mul_f32 v[2:3], v[164:165], v[24:25]
	v_mul_f32_e32 v28, v25, v25
	v_cvt_pk_bf16_f32 v2, v2, v3
	v_cvt_pk_bf16_f32 v3, v0, v1
	v_lshlrev_b32_e32 v0, 4, v155
	v_add3_u32 v0, v146, v0, v147
	ds_write_b64 v0, v[2:3] offset:6144
	s_nop 1
	v_fmac_f32_e32 v28, v24, v24
	v_fmac_f32_e32 v28, v26, v26
	v_fmac_f32_e32 v28, v27, v27
	v_cmp_lt_i32_e32 vcc, v230, v203
	s_waitcnt vmcnt(3)
	v_pk_fma_f32 v[0:1], v[16:17], v[20:21], v[232:233]
	s_nop 0
	v_mul_f32_e32 v16, v1, v1
	v_pk_fma_f32 v[2:3], v[18:19], v[22:23], v[234:235]
	v_fmac_f32_e32 v16, v0, v0
	v_fmac_f32_e32 v16, v2, v2
	global_store_dwordx4 v[34:35], v[0:3], off offset:64
	v_fmac_f32_e32 v16, v3, v3
	v_add_f32_e32 v16, v28, v16
	v_pk_mul_f32 v[2:3], v[158:159], v[2:3]
	v_pk_mul_f32 v[0:1], v[156:157], v[0:1]
	s_nop 0
	v_cvt_pk_bf16_f32 v0, v0, v1
	v_cvt_pk_bf16_f32 v1, v2, v3
	v_lshlrev_b32_e32 v2, 4, v154
	v_add3_u32 v2, v146, v2, v147
	ds_write_b64 v2, v[0:1] offset:6144
	s_nop 1
	s_waitcnt vmcnt(3)
	v_pk_fma_f32 v[0:1], v[8:9], v[12:13], v[236:237]
	s_nop 0
	v_mul_f32_e32 v8, v1, v1
	v_pk_fma_f32 v[2:3], v[10:11], v[14:15], v[238:239]
	v_fmac_f32_e32 v8, v0, v0
	v_fmac_f32_e32 v8, v2, v2
	global_store_dwordx4 v[34:35], v[0:3], off offset:128
	v_fmac_f32_e32 v8, v3, v3
	v_add_f32_e32 v8, v16, v8
	v_pk_mul_f32 v[2:3], v[150:151], v[2:3]
	v_pk_mul_f32 v[0:1], v[148:149], v[0:1]
	s_nop 0
	v_cvt_pk_bf16_f32 v0, v0, v1
	v_cvt_pk_bf16_f32 v1, v2, v3
	v_lshlrev_b32_e32 v2, 4, v153
	v_add3_u32 v2, v146, v2, v147
	ds_write_b64 v2, v[0:1] offset:6144
	s_nop 1
	s_waitcnt vmcnt(3)
	v_pk_fma_f32 v[0:1], v[68:69], v[4:5], v[240:241]
	s_nop 0
	v_mul_f32_e32 v4, v1, v1
	v_pk_fma_f32 v[2:3], v[70:71], v[6:7], v[242:243]
	v_fmac_f32_e32 v4, v0, v0
	v_fmac_f32_e32 v4, v2, v2
	global_store_dwordx4 v[34:35], v[0:3], off offset:192
	v_fmac_f32_e32 v4, v3, v3
	v_add_f32_e32 v4, v8, v4
	v_pk_mul_f32 v[2:3], v[142:143], v[2:3]
	v_pk_mul_f32 v[0:1], v[144:145], v[0:1]
	s_nop 0
	v_cvt_pk_bf16_f32 v0, v0, v1
	v_cvt_pk_bf16_f32 v1, v2, v3
	v_lshlrev_b32_e32 v2, 4, v152
	v_add3_u32 v2, v146, v2, v147
	ds_write_b64 v2, v[0:1] offset:6144
	v_cndmask_b32_e32 v0, v202, v230, vcc
	v_lshlrev_b32_e32 v0, 2, v0
	ds_bpermute_b32 v0, v0, v4
	v_cmp_lt_i32_e32 vcc, v209, v203
	s_waitcnt lgkmcnt(0)
	v_add_f32_e32 v0, v4, v0
	v_cndmask_b32_e32 v1, v202, v209, vcc
	v_lshlrev_b32_e32 v1, 2, v1
	ds_bpermute_b32 v1, v1, v0
	v_cmp_gt_u32_e32 vcc, 16, v185
	s_and_saveexec_b64 s[4:5], vcc
	s_cbranch_execz .LBB0_182
	s_waitcnt lgkmcnt(0)
	v_add_f32_e32 v2, v0, v1
	v_lshlrev_b64 v[0:1], 6, v[32:33]
	v_lshl_add_u64 v[0:1], v[140:141], 0, v[0:1]
	global_store_dword v[0:1], v2, off sc1
	s_branch .LBB0_182
